# GEMM K-loops: the lgkmcnt(8) waits in front of the phase-1/5 barriers removed (the lgkmcnt(0) behind the barrier covers them)
# baseline (speedup 1.0000x reference)
.LBB0_197:
	ds_read_b128 v[144:147], v151
	ds_read_b128 v[154:157], v151 offset:1024
	ds_read_b128 v[158:161], v151 offset:2048
	ds_read_b128 v[162:165], v151 offset:3072
	s_add_u32 s18, s16, 0xfff80080
	s_addc_u32 s19, s17, -1
	s_cmp_eq_u32 s78, 28
	s_cselect_b32 s21, s5, s19
	s_cselect_b32 s20, s9, s18
	s_cselect_b32 s19, s7, s77
	s_cselect_b32 s18, s15, s76
	s_add_i32 m0, s24, 0xc000
	ds_read_b128 v[166:169], v152
	ds_read_b128 v[170:173], v152 offset:1024
	ds_read_b128 v[174:177], v152 offset:2048
	ds_read_b128 v[178:181], v152 offset:3072
	ds_read_b128 v[182:185], v152 offset:4096
	ds_read_b128 v[186:189], v152 offset:5120
	ds_read_b128 v[190:193], v152 offset:6144
	ds_read_b128 v[194:197], v152 offset:7168
	global_load_lds_dwordx4 v136, s[16:17]
	s_add_i32 m0, s24, 0xe000
	s_nop 0
	global_load_lds_dwordx4 v138, s[16:17]
	s_barrier
	s_waitcnt lgkmcnt(0)
	v_mfma_f32_16x16x32_f16 v[124:127], v[144:147], v[166:169], v[124:127]
	v_mfma_f32_16x16x32_f16 v[120:123], v[158:161], v[166:169], v[120:123]
	v_mfma_f32_16x16x32_f16 v[108:111], v[144:147], v[174:177], v[108:111]
	v_mfma_f32_16x16x32_f16 v[104:107], v[158:161], v[174:177], v[104:107]
	v_mfma_f32_16x16x32_f16 v[92:95], v[144:147], v[182:185], v[92:95]
	v_mfma_f32_16x16x32_f16 v[88:91], v[158:161], v[182:185], v[88:91]
	v_mfma_f32_16x16x32_f16 v[76:79], v[144:147], v[190:193], v[76:79]
	v_mfma_f32_16x16x32_f16 v[72:75], v[158:161], v[190:193], v[72:75]
	v_mfma_f32_16x16x32_f16 v[124:127], v[154:157], v[170:173], v[124:127]
	v_mfma_f32_16x16x32_f16 v[120:123], v[162:165], v[170:173], v[120:123]
	v_mfma_f32_16x16x32_f16 v[108:111], v[154:157], v[178:181], v[108:111]
	v_mfma_f32_16x16x32_f16 v[104:107], v[162:165], v[178:181], v[104:107]
	v_mfma_f32_16x16x32_f16 v[92:95], v[154:157], v[186:189], v[92:95]
	v_mfma_f32_16x16x32_f16 v[88:91], v[162:165], v[186:189], v[88:91]
	v_mfma_f32_16x16x32_f16 v[76:79], v[154:157], v[194:197], v[76:79]
	v_mfma_f32_16x16x32_f16 v[72:75], v[162:165], v[194:197], v[72:75]
	s_barrier
	s_add_i32 s79, s68, s23
	s_add_u32 s72, s18, s0
	s_addc_u32 s73, s19, s1
	s_mov_b32 m0, s79
	ds_read_b128 v[198:201], v153
	ds_read_b128 v[202:205], v153 offset:1024
	ds_read_b128 v[206:209], v153 offset:2048
	ds_read_b128 v[210:213], v153 offset:3072
	global_load_lds_dwordx4 v130, s[18:19]
	s_add_i32 m0, s79, 0x2000
	s_nop 0
	global_load_lds_dwordx4 v134, s[18:19]
	s_barrier
	s_waitcnt lgkmcnt(0)
	v_mfma_f32_16x16x32_f16 v[116:119], v[198:201], v[166:169], v[116:119]
	v_mfma_f32_16x16x32_f16 v[112:115], v[206:209], v[166:169], v[112:115]
	v_mfma_f32_16x16x32_f16 v[100:103], v[198:201], v[174:177], v[100:103]
	v_mfma_f32_16x16x32_f16 v[96:99], v[206:209], v[174:177], v[96:99]
	v_mfma_f32_16x16x32_f16 v[84:87], v[198:201], v[182:185], v[84:87]
	v_mfma_f32_16x16x32_f16 v[80:83], v[206:209], v[182:185], v[80:83]
	v_mfma_f32_16x16x32_f16 v[68:71], v[198:201], v[190:193], v[68:71]
	v_mfma_f32_16x16x32_f16 v[64:67], v[206:209], v[190:193], v[64:67]
	v_mfma_f32_16x16x32_f16 v[116:119], v[202:205], v[170:173], v[116:119]
	v_mfma_f32_16x16x32_f16 v[112:115], v[210:213], v[170:173], v[112:115]
	v_mfma_f32_16x16x32_f16 v[100:103], v[202:205], v[178:181], v[100:103]
	v_mfma_f32_16x16x32_f16 v[96:99], v[210:213], v[178:181], v[96:99]
	v_mfma_f32_16x16x32_f16 v[84:87], v[202:205], v[186:189], v[84:87]
	v_mfma_f32_16x16x32_f16 v[80:83], v[210:213], v[186:189], v[80:83]
	v_mfma_f32_16x16x32_f16 v[68:71], v[202:205], v[194:197], v[68:71]
	v_mfma_f32_16x16x32_f16 v[64:67], v[210:213], v[194:197], v[64:67]
	s_barrier
	s_mov_b32 m0, s24
	s_add_u32 s74, s20, s0
	s_addc_u32 s75, s21, s1
	ds_read_b128 v[166:169], v152 offset:16384
	ds_read_b128 v[170:173], v152 offset:17408
	ds_read_b128 v[174:177], v152 offset:18432
	ds_read_b128 v[178:181], v152 offset:19456
	ds_read_b128 v[182:185], v152 offset:20480
	ds_read_b128 v[186:189], v152 offset:21504
	ds_read_b128 v[190:193], v152 offset:22528
	ds_read_b128 v[194:197], v152 offset:23552
	global_load_lds_dwordx4 v128, s[20:21]
	s_mov_b32 m0, s25
	s_nop 0
	global_load_lds_dwordx4 v132, s[20:21]
	s_barrier
	s_waitcnt lgkmcnt(0)
	v_mfma_f32_16x16x32_f16 v[60:63], v[144:147], v[166:169], v[60:63]
	v_mfma_f32_16x16x32_f16 v[56:59], v[158:161], v[166:169], v[56:59]
	v_mfma_f32_16x16x32_f16 v[44:47], v[144:147], v[174:177], v[44:47]
	v_mfma_f32_16x16x32_f16 v[40:43], v[158:161], v[174:177], v[40:43]
	v_mfma_f32_16x16x32_f16 v[28:31], v[144:147], v[182:185], v[28:31]
	v_mfma_f32_16x16x32_f16 v[24:27], v[158:161], v[182:185], v[24:27]
	v_mfma_f32_16x16x32_f16 v[12:15], v[144:147], v[190:193], v[12:15]
	v_mfma_f32_16x16x32_f16 v[8:11], v[158:161], v[190:193], v[8:11]
	v_mfma_f32_16x16x32_f16 v[60:63], v[154:157], v[170:173], v[60:63]
	v_mfma_f32_16x16x32_f16 v[56:59], v[162:165], v[170:173], v[56:59]
	v_mfma_f32_16x16x32_f16 v[44:47], v[154:157], v[178:181], v[44:47]
	v_mfma_f32_16x16x32_f16 v[40:43], v[162:165], v[178:181], v[40:43]
	v_mfma_f32_16x16x32_f16 v[28:31], v[154:157], v[186:189], v[28:31]
	v_mfma_f32_16x16x32_f16 v[24:27], v[162:165], v[186:189], v[24:27]
	v_mfma_f32_16x16x32_f16 v[12:15], v[154:157], v[194:197], v[12:15]
	v_mfma_f32_16x16x32_f16 v[8:11], v[162:165], v[194:197], v[8:11]
	s_barrier
	s_add_u32 s80, s18, 0x80000
	s_addc_u32 s81, s19, 0
	s_add_i32 s79, s69, s23
	s_mov_b32 m0, s79
	s_nop 0
	global_load_lds_dwordx4 v130, s[80:81]
	s_add_i32 m0, s79, 0x2000
	s_nop 0
	global_load_lds_dwordx4 v134, s[80:81]
	s_waitcnt vmcnt(6)
	s_barrier
	v_mfma_f32_16x16x32_f16 v[52:55], v[198:201], v[166:169], v[52:55]
	v_mfma_f32_16x16x32_f16 v[48:51], v[206:209], v[166:169], v[48:51]
	v_mfma_f32_16x16x32_f16 v[36:39], v[198:201], v[174:177], v[36:39]
	v_mfma_f32_16x16x32_f16 v[32:35], v[206:209], v[174:177], v[32:35]
	v_mfma_f32_16x16x32_f16 v[20:23], v[198:201], v[182:185], v[20:23]
	v_mfma_f32_16x16x32_f16 v[16:19], v[206:209], v[182:185], v[16:19]
	v_mfma_f32_16x16x32_f16 v[4:7], v[198:201], v[190:193], v[4:7]
	v_mfma_f32_16x16x32_f16 v[0:3], v[206:209], v[190:193], v[0:3]
	v_mfma_f32_16x16x32_f16 v[52:55], v[202:205], v[170:173], v[52:55]
	v_mfma_f32_16x16x32_f16 v[48:51], v[210:213], v[170:173], v[48:51]
	v_mfma_f32_16x16x32_f16 v[36:39], v[202:205], v[178:181], v[36:39]
	v_mfma_f32_16x16x32_f16 v[32:35], v[210:213], v[178:181], v[32:35]
	v_mfma_f32_16x16x32_f16 v[20:23], v[202:205], v[186:189], v[20:23]
	v_mfma_f32_16x16x32_f16 v[16:19], v[210:213], v[186:189], v[16:19]
	v_mfma_f32_16x16x32_f16 v[4:7], v[202:205], v[194:197], v[4:7]
	v_mfma_f32_16x16x32_f16 v[0:3], v[210:213], v[194:197], v[0:3]
	s_barrier
	s_add_i32 s79, 0, 0x18000
	v_add_u32_e32 v162, s79, v149
	ds_read_b128 v[144:147], v162
	ds_read_b128 v[154:157], v162 offset:1024
	ds_read_b128 v[158:161], v162 offset:2048
	ds_read_b128 v[162:165], v162 offset:3072
	s_add_u32 s20, s20, 0x80000
	s_addc_u32 s21, s21, 0
	s_mov_b32 m0, s26
	ds_read_b128 v[166:169], v152 offset:32768
	ds_read_b128 v[170:173], v152 offset:33792
	ds_read_b128 v[174:177], v152 offset:34816
	ds_read_b128 v[178:181], v152 offset:35840
	ds_read_b128 v[182:185], v152 offset:36864
	ds_read_b128 v[186:189], v152 offset:37888
	ds_read_b128 v[190:193], v152 offset:38912
	ds_read_b128 v[194:197], v152 offset:39936
	global_load_lds_dwordx4 v128, s[20:21]
	s_mov_b32 m0, s27
	s_nop 0
	global_load_lds_dwordx4 v132, s[20:21]
	s_barrier
	s_waitcnt lgkmcnt(0)
	v_mfma_f32_16x16x32_f16 v[124:127], v[144:147], v[166:169], v[124:127]
	v_mfma_f32_16x16x32_f16 v[120:123], v[158:161], v[166:169], v[120:123]
	v_mfma_f32_16x16x32_f16 v[108:111], v[144:147], v[174:177], v[108:111]
	v_mfma_f32_16x16x32_f16 v[104:107], v[158:161], v[174:177], v[104:107]
	v_mfma_f32_16x16x32_f16 v[92:95], v[144:147], v[182:185], v[92:95]
	v_mfma_f32_16x16x32_f16 v[88:91], v[158:161], v[182:185], v[88:91]
	v_mfma_f32_16x16x32_f16 v[76:79], v[144:147], v[190:193], v[76:79]
	v_mfma_f32_16x16x32_f16 v[72:75], v[158:161], v[190:193], v[72:75]
	v_mfma_f32_16x16x32_f16 v[124:127], v[154:157], v[170:173], v[124:127]
	v_mfma_f32_16x16x32_f16 v[120:123], v[162:165], v[170:173], v[120:123]
	v_mfma_f32_16x16x32_f16 v[108:111], v[154:157], v[178:181], v[108:111]
	v_mfma_f32_16x16x32_f16 v[104:107], v[162:165], v[178:181], v[104:107]
	v_mfma_f32_16x16x32_f16 v[92:95], v[154:157], v[186:189], v[92:95]
	v_mfma_f32_16x16x32_f16 v[88:91], v[162:165], v[186:189], v[88:91]
	v_mfma_f32_16x16x32_f16 v[76:79], v[154:157], v[194:197], v[76:79]
	v_mfma_f32_16x16x32_f16 v[72:75], v[162:165], v[194:197], v[72:75]
	s_barrier
	s_add_i32 s20, 0, 0x1c000
	s_add_i32 s21, s79, s23
	v_add_u32_e32 v210, s20, v149
	s_mov_b32 m0, s21
	ds_read_b128 v[198:201], v210
	ds_read_b128 v[202:205], v210 offset:1024
	ds_read_b128 v[206:209], v210 offset:2048
	ds_read_b128 v[210:213], v210 offset:3072
	global_load_lds_dwordx4 v130, s[72:73]
	s_add_i32 m0, s21, 0x2000
	s_nop 0
	global_load_lds_dwordx4 v134, s[72:73]
	s_barrier
	s_waitcnt lgkmcnt(0)
	v_mfma_f32_16x16x32_f16 v[116:119], v[198:201], v[166:169], v[116:119]
	v_mfma_f32_16x16x32_f16 v[112:115], v[206:209], v[166:169], v[112:115]
	v_mfma_f32_16x16x32_f16 v[100:103], v[198:201], v[174:177], v[100:103]
	v_mfma_f32_16x16x32_f16 v[96:99], v[206:209], v[174:177], v[96:99]
	v_mfma_f32_16x16x32_f16 v[84:87], v[198:201], v[182:185], v[84:87]
	v_mfma_f32_16x16x32_f16 v[80:83], v[206:209], v[182:185], v[80:83]
	v_mfma_f32_16x16x32_f16 v[68:71], v[198:201], v[190:193], v[68:71]
	v_mfma_f32_16x16x32_f16 v[64:67], v[206:209], v[190:193], v[64:67]
	v_mfma_f32_16x16x32_f16 v[116:119], v[202:205], v[170:173], v[116:119]
	v_mfma_f32_16x16x32_f16 v[112:115], v[210:213], v[170:173], v[112:115]
	v_mfma_f32_16x16x32_f16 v[100:103], v[202:205], v[178:181], v[100:103]
	v_mfma_f32_16x16x32_f16 v[96:99], v[210:213], v[178:181], v[96:99]
	v_mfma_f32_16x16x32_f16 v[84:87], v[202:205], v[186:189], v[84:87]
	v_mfma_f32_16x16x32_f16 v[80:83], v[210:213], v[186:189], v[80:83]
	v_mfma_f32_16x16x32_f16 v[68:71], v[202:205], v[194:197], v[68:71]
	v_mfma_f32_16x16x32_f16 v[64:67], v[210:213], v[194:197], v[64:67]
	s_barrier
	s_mov_b32 m0, s29
	ds_read_b128 v[166:169], v152 offset:49152
	ds_read_b128 v[170:173], v152 offset:50176
	ds_read_b128 v[174:177], v152 offset:51200
	ds_read_b128 v[178:181], v152 offset:52224
	ds_read_b128 v[182:185], v152 offset:53248
	ds_read_b128 v[186:189], v152 offset:54272
	ds_read_b128 v[190:193], v152 offset:55296
	ds_read_b128 v[194:197], v152 offset:56320
	global_load_lds_dwordx4 v128, s[74:75]
	s_mov_b32 m0, s30
	s_nop 0
	global_load_lds_dwordx4 v132, s[74:75]
	s_barrier
	s_waitcnt lgkmcnt(0)
	v_mfma_f32_16x16x32_f16 v[60:63], v[144:147], v[166:169], v[60:63]
	v_mfma_f32_16x16x32_f16 v[56:59], v[158:161], v[166:169], v[56:59]
	v_mfma_f32_16x16x32_f16 v[44:47], v[144:147], v[174:177], v[44:47]
	v_mfma_f32_16x16x32_f16 v[40:43], v[158:161], v[174:177], v[40:43]
	v_mfma_f32_16x16x32_f16 v[28:31], v[144:147], v[182:185], v[28:31]
	v_mfma_f32_16x16x32_f16 v[24:27], v[158:161], v[182:185], v[24:27]
	v_mfma_f32_16x16x32_f16 v[12:15], v[144:147], v[190:193], v[12:15]
	v_mfma_f32_16x16x32_f16 v[8:11], v[158:161], v[190:193], v[8:11]
	v_mfma_f32_16x16x32_f16 v[60:63], v[154:157], v[170:173], v[60:63]
	v_mfma_f32_16x16x32_f16 v[56:59], v[162:165], v[170:173], v[56:59]
	v_mfma_f32_16x16x32_f16 v[44:47], v[154:157], v[178:181], v[44:47]
	v_mfma_f32_16x16x32_f16 v[40:43], v[162:165], v[178:181], v[40:43]
	v_mfma_f32_16x16x32_f16 v[28:31], v[154:157], v[186:189], v[28:31]
	v_mfma_f32_16x16x32_f16 v[24:27], v[162:165], v[186:189], v[24:27]
	v_mfma_f32_16x16x32_f16 v[12:15], v[154:157], v[194:197], v[12:15]
	v_mfma_f32_16x16x32_f16 v[8:11], v[162:165], v[194:197], v[8:11]
	s_barrier
	s_add_u32 s18, s18, 0x80080
	s_addc_u32 s19, s19, 0
	s_add_i32 s20, s20, s23
	s_mov_b32 m0, s20
	s_nop 0
	global_load_lds_dwordx4 v130, s[18:19]
	s_add_i32 m0, s20, 0x2000
	s_nop 0
	global_load_lds_dwordx4 v134, s[18:19]
	s_waitcnt vmcnt(6)
	s_barrier
	v_mfma_f32_16x16x32_f16 v[52:55], v[198:201], v[166:169], v[52:55]
	v_mfma_f32_16x16x32_f16 v[48:51], v[206:209], v[166:169], v[48:51]
	v_mfma_f32_16x16x32_f16 v[36:39], v[198:201], v[174:177], v[36:39]
	v_mfma_f32_16x16x32_f16 v[32:35], v[206:209], v[174:177], v[32:35]
	v_mfma_f32_16x16x32_f16 v[20:23], v[198:201], v[182:185], v[20:23]
	v_mfma_f32_16x16x32_f16 v[16:19], v[206:209], v[182:185], v[16:19]
	v_mfma_f32_16x16x32_f16 v[4:7], v[198:201], v[190:193], v[4:7]
	v_mfma_f32_16x16x32_f16 v[0:3], v[206:209], v[190:193], v[0:3]
	v_mfma_f32_16x16x32_f16 v[52:55], v[202:205], v[170:173], v[52:55]
	v_mfma_f32_16x16x32_f16 v[48:51], v[210:213], v[170:173], v[48:51]
	v_mfma_f32_16x16x32_f16 v[36:39], v[202:205], v[178:181], v[36:39]
	v_mfma_f32_16x16x32_f16 v[32:35], v[210:213], v[178:181], v[32:35]
	v_mfma_f32_16x16x32_f16 v[20:23], v[202:205], v[186:189], v[20:23]
	v_mfma_f32_16x16x32_f16 v[16:19], v[210:213], v[186:189], v[16:19]
	v_mfma_f32_16x16x32_f16 v[4:7], v[202:205], v[194:197], v[4:7]
	v_mfma_f32_16x16x32_f16 v[0:3], v[210:213], v[194:197], v[0:3]
	s_barrier
	s_add_i32 s78, s78, 2
	s_add_u32 s16, s16, 0x100
	s_addc_u32 s17, s17, 0
	s_add_u32 s76, s76, 0x100
	s_addc_u32 s77, s77, 0
	s_cmp_gt_u32 s78, 29
	s_cbranch_scc0 .LBB0_197
	s_setprio 0
	v_readlane_b32 s52, v254, 21
	v_readlane_b32 s54, v254, 23
	v_readlane_b32 s55, v254, 24
	v_lshl_add_u32 v154, s14, 8, v148
	v_lshl_or_b32 v144, s4, 8, v150
	v_mov_b64_e32 v[146:147], s[54:55]
	v_mad_i64_i32 v[146:147], s[4:5], v154, s70, v[146:147]
	v_cmp_gt_i32_e32 vcc, s71, v144
	v_ashrrev_i32_e32 v145, 31, v144
	v_readlane_b32 s53, v254, 22
	v_readlane_b32 s56, v254, 25
	v_readlane_b32 s57, v254, 26
	v_readlane_b32 s58, v254, 27
	v_readlane_b32 s59, v254, 28
	v_readlane_b32 s60, v254, 29
	v_readlane_b32 s61, v254, 30
	v_readlane_b32 s62, v254, 31
	v_readlane_b32 s63, v254, 32
	v_readlane_b32 s64, v254, 33
	v_readlane_b32 s65, v254, 34
	v_readlane_b32 s66, v254, 35
	v_readlane_b32 s67, v254, 36
	s_and_saveexec_b64 s[4:5], vcc
	s_cbranch_execz .LBB0_200
	v_cvt_pk_f16_f32 v123, v122, v123
	v_cvt_pk_f16_f32 v122, v120, v121
	v_cvt_pk_f16_f32 v121, v126, v127
	v_cvt_pk_f16_f32 v120, v124, v125
	v_lshl_add_u64 v[124:125], v[144:145], 1, v[146:147]
	global_store_dwordx4 v[124:125], v[120:123], off

.LBB0_647:
	ds_read_b128 v[80:83], v243
	ds_read_b128 v[88:91], v243 offset:1024
	ds_read_b128 v[96:99], v243 offset:2048
	ds_read_b128 v[100:103], v243 offset:3072
	s_add_u32 s18, s16, 0xfff80080
	s_addc_u32 s19, s17, -1
	s_cmp_eq_u32 s80, 28
	s_cselect_b32 s21, s9, s19
	s_cselect_b32 s20, s31, s18
	s_cselect_b32 s19, s7, s79
	s_cselect_b32 s18, s77, s78
	s_add_i32 m0, s15, 0xc000
	ds_read_b128 v[120:123], v244
	ds_read_b128 v[132:135], v244 offset:1024
	ds_read_b128 v[136:139], v244 offset:2048
	ds_read_b128 v[148:151], v244 offset:3072
	ds_read_b128 v[152:155], v244 offset:4096
	ds_read_b128 v[156:159], v244 offset:5120
	ds_read_b128 v[160:163], v244 offset:6144
	ds_read_b128 v[172:175], v244 offset:7168
	global_load_lds_dwordx4 v212, s[16:17]
	s_add_i32 m0, s15, 0xe000
	s_nop 0
	global_load_lds_dwordx4 v214, s[16:17]
	s_barrier
	s_waitcnt lgkmcnt(0)
	v_mfma_f32_16x16x32_f16 v[168:171], v[80:83], v[120:123], v[168:171]
	v_mfma_f32_16x16x32_f16 v[164:167], v[96:99], v[120:123], v[164:167]
	v_mfma_f32_16x16x32_f16 v[128:131], v[80:83], v[136:139], v[128:131]
	v_mfma_f32_16x16x32_f16 v[124:127], v[96:99], v[136:139], v[124:127]
	v_mfma_f32_16x16x32_f16 v[108:111], v[80:83], v[152:155], v[108:111]
	v_mfma_f32_16x16x32_f16 v[104:107], v[96:99], v[152:155], v[104:107]
	v_mfma_f32_16x16x32_f16 v[76:79], v[80:83], v[160:163], v[76:79]
	v_mfma_f32_16x16x32_f16 v[72:75], v[96:99], v[160:163], v[72:75]
	v_mfma_f32_16x16x32_f16 v[168:171], v[88:91], v[132:135], v[168:171]
	v_mfma_f32_16x16x32_f16 v[164:167], v[100:103], v[132:135], v[164:167]
	v_mfma_f32_16x16x32_f16 v[128:131], v[88:91], v[148:151], v[128:131]
	v_mfma_f32_16x16x32_f16 v[124:127], v[100:103], v[148:151], v[124:127]
	v_mfma_f32_16x16x32_f16 v[108:111], v[88:91], v[156:159], v[108:111]
	v_mfma_f32_16x16x32_f16 v[104:107], v[100:103], v[156:159], v[104:107]
	v_mfma_f32_16x16x32_f16 v[76:79], v[88:91], v[172:175], v[76:79]
	v_mfma_f32_16x16x32_f16 v[72:75], v[100:103], v[172:175], v[72:75]
	s_barrier
	s_add_i32 s81, s71, s24
	s_add_u32 s72, s18, s4
	s_addc_u32 s73, s19, s5
	s_mov_b32 m0, s81
	ds_read_b128 v[176:179], v245
	ds_read_b128 v[180:183], v245 offset:1024
	ds_read_b128 v[184:187], v245 offset:2048
	ds_read_b128 v[188:191], v245 offset:3072
	global_load_lds_dwordx4 v206, s[18:19]
	s_add_i32 m0, s81, 0x2000
	s_nop 0
	global_load_lds_dwordx4 v210, s[18:19]
	s_barrier
	s_waitcnt lgkmcnt(0)
	v_mfma_f32_16x16x32_f16 v[144:147], v[176:179], v[120:123], v[144:147]
	v_mfma_f32_16x16x32_f16 v[116:119], v[176:179], v[136:139], v[116:119]
	v_mfma_f32_16x16x32_f16 v[112:115], v[184:187], v[136:139], v[112:115]
	v_mfma_f32_16x16x32_f16 v[92:95], v[176:179], v[152:155], v[92:95]
	v_mfma_f32_16x16x32_f16 v[84:87], v[184:187], v[152:155], v[84:87]
	v_mfma_f32_16x16x32_f16 v[68:71], v[176:179], v[160:163], v[68:71]
	v_mfma_f32_16x16x32_f16 v[64:67], v[184:187], v[160:163], v[64:67]
	v_mfma_f32_16x16x32_f16 v[144:147], v[180:183], v[132:135], v[144:147]
	v_mfma_f32_16x16x32_f16 v[120:123], v[184:187], v[120:123], v[140:143]
	v_mfma_f32_16x16x32_f16 v[116:119], v[180:183], v[148:151], v[116:119]
	v_mfma_f32_16x16x32_f16 v[112:115], v[188:191], v[148:151], v[112:115]
	v_mfma_f32_16x16x32_f16 v[92:95], v[180:183], v[156:159], v[92:95]
	v_mfma_f32_16x16x32_f16 v[84:87], v[188:191], v[156:159], v[84:87]
	v_mfma_f32_16x16x32_f16 v[68:71], v[180:183], v[172:175], v[68:71]
	v_mfma_f32_16x16x32_f16 v[64:67], v[188:191], v[172:175], v[64:67]
	v_mfma_f32_16x16x32_f16 v[120:123], v[188:191], v[132:135], v[120:123]
	s_barrier
	s_mov_b32 m0, s15
	s_add_u32 s74, s20, s4
	s_addc_u32 s75, s21, s5
	ds_read_b128 v[132:135], v244 offset:16384
	ds_read_b128 v[136:139], v244 offset:17408
	ds_read_b128 v[140:143], v244 offset:18432
	ds_read_b128 v[148:151], v244 offset:19456
	ds_read_b128 v[152:155], v244 offset:20480
	ds_read_b128 v[156:159], v244 offset:21504
	ds_read_b128 v[160:163], v244 offset:22528
	ds_read_b128 v[172:175], v244 offset:23552
	global_load_lds_dwordx4 v204, s[20:21]
	s_mov_b32 m0, s25
	s_nop 0
	global_load_lds_dwordx4 v208, s[20:21]
	s_barrier
	s_waitcnt lgkmcnt(0)
	v_mfma_f32_16x16x32_f16 v[60:63], v[80:83], v[132:135], v[60:63]
	v_mfma_f32_16x16x32_f16 v[56:59], v[96:99], v[132:135], v[56:59]
	v_mfma_f32_16x16x32_f16 v[44:47], v[80:83], v[140:143], v[44:47]
	v_mfma_f32_16x16x32_f16 v[40:43], v[96:99], v[140:143], v[40:43]
	v_mfma_f32_16x16x32_f16 v[28:31], v[80:83], v[152:155], v[28:31]
	v_mfma_f32_16x16x32_f16 v[24:27], v[96:99], v[152:155], v[24:27]
	v_mfma_f32_16x16x32_f16 v[12:15], v[80:83], v[160:163], v[12:15]
	v_mfma_f32_16x16x32_f16 v[8:11], v[96:99], v[160:163], v[8:11]
	v_mfma_f32_16x16x32_f16 v[60:63], v[88:91], v[136:139], v[60:63]
	v_mfma_f32_16x16x32_f16 v[56:59], v[100:103], v[136:139], v[56:59]
	v_mfma_f32_16x16x32_f16 v[44:47], v[88:91], v[148:151], v[44:47]
	v_mfma_f32_16x16x32_f16 v[40:43], v[100:103], v[148:151], v[40:43]
	v_mfma_f32_16x16x32_f16 v[28:31], v[88:91], v[156:159], v[28:31]
	v_mfma_f32_16x16x32_f16 v[24:27], v[100:103], v[156:159], v[24:27]
	v_mfma_f32_16x16x32_f16 v[12:15], v[88:91], v[172:175], v[12:15]
	v_mfma_f32_16x16x32_f16 v[8:11], v[100:103], v[172:175], v[8:11]
	s_barrier
	s_add_u32 s82, s18, 0x80000
	s_addc_u32 s83, s19, 0
	s_add_i32 s81, s76, s24
	s_mov_b32 m0, s81
	s_nop 0
	global_load_lds_dwordx4 v206, s[82:83]
	s_add_i32 m0, s81, 0x2000
	s_nop 0
	global_load_lds_dwordx4 v210, s[82:83]
	s_waitcnt vmcnt(6)
	s_barrier
	v_mfma_f32_16x16x32_f16 v[52:55], v[176:179], v[132:135], v[52:55]
	v_mfma_f32_16x16x32_f16 v[48:51], v[184:187], v[132:135], v[48:51]
	v_mfma_f32_16x16x32_f16 v[36:39], v[176:179], v[140:143], v[36:39]
	v_mfma_f32_16x16x32_f16 v[32:35], v[184:187], v[140:143], v[32:35]
	v_mfma_f32_16x16x32_f16 v[20:23], v[176:179], v[152:155], v[20:23]
	v_mfma_f32_16x16x32_f16 v[16:19], v[184:187], v[152:155], v[16:19]
	v_mfma_f32_16x16x32_f16 v[4:7], v[176:179], v[160:163], v[4:7]
	v_mfma_f32_16x16x32_f16 v[0:3], v[184:187], v[160:163], v[0:3]
	v_mfma_f32_16x16x32_f16 v[52:55], v[180:183], v[136:139], v[52:55]
	v_mfma_f32_16x16x32_f16 v[48:51], v[188:191], v[136:139], v[48:51]
	v_mfma_f32_16x16x32_f16 v[36:39], v[180:183], v[148:151], v[36:39]
	v_mfma_f32_16x16x32_f16 v[32:35], v[188:191], v[148:151], v[32:35]
	v_mfma_f32_16x16x32_f16 v[20:23], v[180:183], v[156:159], v[20:23]
	v_mfma_f32_16x16x32_f16 v[16:19], v[188:191], v[156:159], v[16:19]
	v_mfma_f32_16x16x32_f16 v[4:7], v[180:183], v[172:175], v[4:7]
	v_mfma_f32_16x16x32_f16 v[0:3], v[188:191], v[172:175], v[0:3]
	s_barrier
	s_add_i32 s81, 0, 0x18000
	v_add_u32_e32 v100, s81, v241
	ds_read_b128 v[80:83], v100
	ds_read_b128 v[88:91], v100 offset:1024
	ds_read_b128 v[96:99], v100 offset:2048
	ds_read_b128 v[100:103], v100 offset:3072
	s_add_u32 s20, s20, 0x80000
	s_addc_u32 s21, s21, 0
	s_mov_b32 m0, s26
	ds_read_b128 v[132:135], v244 offset:32768
	ds_read_b128 v[136:139], v244 offset:33792
	ds_read_b128 v[148:151], v244 offset:34816
	ds_read_b128 v[152:155], v244 offset:35840
	ds_read_b128 v[156:159], v244 offset:36864
	ds_read_b128 v[160:163], v244 offset:37888
	ds_read_b128 v[172:175], v244 offset:38912
	ds_read_b128 v[176:179], v244 offset:39936
	global_load_lds_dwordx4 v204, s[20:21]
	s_mov_b32 m0, s27
	s_nop 0
	global_load_lds_dwordx4 v208, s[20:21]
	s_barrier
	s_waitcnt lgkmcnt(0)
	v_mfma_f32_16x16x32_f16 v[140:143], v[80:83], v[132:135], v[168:171]
	v_mfma_f32_16x16x32_f16 v[168:171], v[88:91], v[136:139], v[140:143]
	v_mfma_f32_16x16x32_f16 v[140:143], v[96:99], v[132:135], v[164:167]
	v_mfma_f32_16x16x32_f16 v[128:131], v[80:83], v[148:151], v[128:131]
	v_mfma_f32_16x16x32_f16 v[124:127], v[96:99], v[148:151], v[124:127]
	v_mfma_f32_16x16x32_f16 v[108:111], v[80:83], v[156:159], v[108:111]
	v_mfma_f32_16x16x32_f16 v[104:107], v[96:99], v[156:159], v[104:107]
	v_mfma_f32_16x16x32_f16 v[76:79], v[80:83], v[172:175], v[76:79]
	v_mfma_f32_16x16x32_f16 v[72:75], v[96:99], v[172:175], v[72:75]
	v_mfma_f32_16x16x32_f16 v[164:167], v[100:103], v[136:139], v[140:143]
	v_mfma_f32_16x16x32_f16 v[128:131], v[88:91], v[152:155], v[128:131]
	v_mfma_f32_16x16x32_f16 v[124:127], v[100:103], v[152:155], v[124:127]
	v_mfma_f32_16x16x32_f16 v[108:111], v[88:91], v[160:163], v[108:111]
	v_mfma_f32_16x16x32_f16 v[104:107], v[100:103], v[160:163], v[104:107]
	v_mfma_f32_16x16x32_f16 v[76:79], v[88:91], v[176:179], v[76:79]
	v_mfma_f32_16x16x32_f16 v[72:75], v[100:103], v[176:179], v[72:75]
	s_barrier
	s_add_i32 s20, 0, 0x1c000
	v_add_u32_e32 v140, s20, v241
	s_add_i32 s21, s81, s24
	ds_read_b128 v[180:183], v140
	ds_read_b128 v[184:187], v140 offset:1024
	ds_read_b128 v[188:191], v140 offset:2048
	ds_read_b128 v[192:195], v140 offset:3072
	s_mov_b32 m0, s21
	s_nop 0
	global_load_lds_dwordx4 v206, s[72:73]
	s_add_i32 m0, s21, 0x2000
	s_nop 0
	global_load_lds_dwordx4 v210, s[72:73]
	s_barrier
	s_waitcnt lgkmcnt(0)
	v_mfma_f32_16x16x32_f16 v[140:143], v[180:183], v[132:135], v[144:147]
	v_mfma_f32_16x16x32_f16 v[120:123], v[188:191], v[132:135], v[120:123]
	v_mfma_f32_16x16x32_f16 v[116:119], v[180:183], v[148:151], v[116:119]
	v_mfma_f32_16x16x32_f16 v[112:115], v[188:191], v[148:151], v[112:115]
	v_mfma_f32_16x16x32_f16 v[92:95], v[180:183], v[156:159], v[92:95]
	v_mfma_f32_16x16x32_f16 v[84:87], v[188:191], v[156:159], v[84:87]
	v_mfma_f32_16x16x32_f16 v[68:71], v[180:183], v[172:175], v[68:71]
	v_mfma_f32_16x16x32_f16 v[64:67], v[188:191], v[172:175], v[64:67]
	v_mfma_f32_16x16x32_f16 v[144:147], v[184:187], v[136:139], v[140:143]
	v_mfma_f32_16x16x32_f16 v[140:143], v[192:195], v[136:139], v[120:123]
	v_mfma_f32_16x16x32_f16 v[116:119], v[184:187], v[152:155], v[116:119]
	v_mfma_f32_16x16x32_f16 v[112:115], v[192:195], v[152:155], v[112:115]
	v_mfma_f32_16x16x32_f16 v[92:95], v[184:187], v[160:163], v[92:95]
	v_mfma_f32_16x16x32_f16 v[84:87], v[192:195], v[160:163], v[84:87]
	v_mfma_f32_16x16x32_f16 v[68:71], v[184:187], v[176:179], v[68:71]
	v_mfma_f32_16x16x32_f16 v[64:67], v[192:195], v[176:179], v[64:67]
	s_barrier
	s_mov_b32 m0, s35
	ds_read_b128 v[120:123], v244 offset:49152
	ds_read_b128 v[132:135], v244 offset:50176
	ds_read_b128 v[136:139], v244 offset:51200
	ds_read_b128 v[148:151], v244 offset:52224
	ds_read_b128 v[152:155], v244 offset:53248
	ds_read_b128 v[156:159], v244 offset:54272
	ds_read_b128 v[160:163], v244 offset:55296
	ds_read_b128 v[172:175], v244 offset:56320
	global_load_lds_dwordx4 v204, s[74:75]
	s_mov_b32 m0, s68
	s_nop 0
	global_load_lds_dwordx4 v208, s[74:75]
	s_barrier
	s_waitcnt lgkmcnt(0)
	v_mfma_f32_16x16x32_f16 v[60:63], v[80:83], v[120:123], v[60:63]
	v_mfma_f32_16x16x32_f16 v[56:59], v[96:99], v[120:123], v[56:59]
	v_mfma_f32_16x16x32_f16 v[44:47], v[80:83], v[136:139], v[44:47]
	v_mfma_f32_16x16x32_f16 v[40:43], v[96:99], v[136:139], v[40:43]
	v_mfma_f32_16x16x32_f16 v[28:31], v[80:83], v[152:155], v[28:31]
	v_mfma_f32_16x16x32_f16 v[24:27], v[96:99], v[152:155], v[24:27]
	v_mfma_f32_16x16x32_f16 v[12:15], v[80:83], v[160:163], v[12:15]
	v_mfma_f32_16x16x32_f16 v[8:11], v[96:99], v[160:163], v[8:11]
	v_mfma_f32_16x16x32_f16 v[60:63], v[88:91], v[132:135], v[60:63]
	v_mfma_f32_16x16x32_f16 v[56:59], v[100:103], v[132:135], v[56:59]
	v_mfma_f32_16x16x32_f16 v[44:47], v[88:91], v[148:151], v[44:47]
	v_mfma_f32_16x16x32_f16 v[40:43], v[100:103], v[148:151], v[40:43]
	v_mfma_f32_16x16x32_f16 v[28:31], v[88:91], v[156:159], v[28:31]
	v_mfma_f32_16x16x32_f16 v[24:27], v[100:103], v[156:159], v[24:27]
	v_mfma_f32_16x16x32_f16 v[12:15], v[88:91], v[172:175], v[12:15]
	v_mfma_f32_16x16x32_f16 v[8:11], v[100:103], v[172:175], v[8:11]
	s_barrier
	s_add_u32 s18, s18, 0x80080
	s_addc_u32 s19, s19, 0
	s_add_i32 s20, s20, s24
	s_mov_b32 m0, s20
	s_nop 0
	global_load_lds_dwordx4 v206, s[18:19]
	s_add_i32 m0, s20, 0x2000
	s_nop 0
	global_load_lds_dwordx4 v210, s[18:19]
	s_waitcnt vmcnt(6)
	s_barrier
	v_mfma_f32_16x16x32_f16 v[52:55], v[180:183], v[120:123], v[52:55]
	v_mfma_f32_16x16x32_f16 v[48:51], v[188:191], v[120:123], v[48:51]
	v_mfma_f32_16x16x32_f16 v[36:39], v[180:183], v[136:139], v[36:39]
	v_mfma_f32_16x16x32_f16 v[32:35], v[188:191], v[136:139], v[32:35]
	v_mfma_f32_16x16x32_f16 v[20:23], v[180:183], v[152:155], v[20:23]
	v_mfma_f32_16x16x32_f16 v[16:19], v[188:191], v[152:155], v[16:19]
	v_mfma_f32_16x16x32_f16 v[4:7], v[180:183], v[160:163], v[4:7]
	v_mfma_f32_16x16x32_f16 v[0:3], v[188:191], v[160:163], v[0:3]
	v_mfma_f32_16x16x32_f16 v[52:55], v[184:187], v[132:135], v[52:55]
	v_mfma_f32_16x16x32_f16 v[48:51], v[192:195], v[132:135], v[48:51]
	v_mfma_f32_16x16x32_f16 v[36:39], v[184:187], v[148:151], v[36:39]
	v_mfma_f32_16x16x32_f16 v[32:35], v[192:195], v[148:151], v[32:35]
	v_mfma_f32_16x16x32_f16 v[20:23], v[184:187], v[156:159], v[20:23]
	v_mfma_f32_16x16x32_f16 v[16:19], v[192:195], v[156:159], v[16:19]
	v_mfma_f32_16x16x32_f16 v[4:7], v[184:187], v[172:175], v[4:7]
	v_mfma_f32_16x16x32_f16 v[0:3], v[192:195], v[172:175], v[0:3]
	s_barrier
	s_add_i32 s80, s80, 2
	s_add_u32 s16, s16, 0x100
	s_addc_u32 s17, s17, 0
	s_add_u32 s78, s78, 0x100
	s_addc_u32 s79, s79, 0
	s_cmp_gt_u32 s80, 29
	s_cbranch_scc0 .LBB0_647
	s_setprio 0
	s_lshl_b32 s7, s14, 8
	s_add_i32 s9, s7, 0xffffe000
	s_lshr_b32 s9, s9, 11
	s_mulk_i32 s9, 0x1800
	s_addk_i32 s9, 0x1800
	s_cmp_gt_i32 s14, 31
	s_cselect_b32 s16, s9, 0
	s_ashr_i32 s17, s16, 31
	v_lshl_or_b32 v120, s30, 8, v242
	s_lshl_b64 s[16:17], s[16:17], 2
	s_add_u32 s16, s29, s16
	v_ashrrev_i32_e32 v121, 31, v120
	v_add_u32_e32 v122, s7, v240
	s_addc_u32 s17, s34, s17
	v_lshlrev_b64 v[220:221], 1, v[120:121]
	v_ashrrev_i32_e32 v123, 31, v122
	v_lshl_add_u64 v[88:89], v[120:121], 2, s[16:17]
	v_lshl_add_u64 v[120:121], s[40:41], 0, v[220:221]
	v_lshlrev_b64 v[236:237], 12, v[122:123]
	v_lshl_add_u64 v[132:133], v[120:121], 0, v[236:237]
	global_load_dwordx4 v[96:99], v[88:89], off offset:16
	global_load_dwordx4 v[100:103], v[88:89], off
	global_load_dwordx4 v[80:83], v[88:89], off offset:528
	s_nop 0
	global_load_dwordx4 v[88:91], v[88:89], off offset:512
	s_nop 0
	global_load_dwordx4 v[246:249], v[132:133], off nt
	global_load_dwordx4 v[200:203], v[132:133], off offset:256 nt
	v_or_b32_e32 v132, 16, v122
	v_ashrrev_i32_e32 v133, 31, v132
	v_lshlrev_b64 v[234:235], 12, v[132:133]
	v_lshl_add_u64 v[132:133], v[120:121], 0, v[234:235]
	global_load_dwordx4 v[196:199], v[132:133], off nt
	global_load_dwordx4 v[192:195], v[132:133], off offset:256 nt
	v_or_b32_e32 v132, 32, v122
	v_ashrrev_i32_e32 v133, 31, v132
	v_lshlrev_b64 v[232:233], 12, v[132:133]
	v_lshl_add_u64 v[132:133], v[120:121], 0, v[232:233]
	global_load_dwordx4 v[188:191], v[132:133], off nt
	global_load_dwordx4 v[184:187], v[132:133], off offset:256 nt
	v_or_b32_e32 v122, 48, v122
	v_ashrrev_i32_e32 v123, 31, v122
	v_lshlrev_b64 v[230:231], 12, v[122:123]
	v_lshl_add_u64 v[122:123], v[120:121], 0, v[230:231]
	global_load_dwordx4 v[180:183], v[122:123], off nt
	global_load_dwordx4 v[176:179], v[122:123], off offset:256 nt
	s_mov_b64 s[16:17], 0x80000
	v_lshl_add_u64 v[228:229], v[236:237], 0, s[16:17]
	v_lshl_add_u64 v[122:123], v[120:121], 0, v[228:229]
	global_load_dwordx4 v[172:175], v[122:123], off nt
	global_load_dwordx4 v[160:163], v[122:123], off offset:256 nt
	s_mov_b64 s[16:17], 0x90000
	v_lshl_add_u64 v[226:227], v[236:237], 0, s[16:17]
	v_lshl_add_u64 v[122:123], v[120:121], 0, v[226:227]
	global_load_dwordx4 v[156:159], v[122:123], off nt
	global_load_dwordx4 v[152:155], v[122:123], off offset:256 nt
	s_mov_b64 s[16:17], 0xa0000
	v_lshl_add_u64 v[224:225], v[236:237], 0, s[16:17]
	v_lshl_add_u64 v[122:123], v[120:121], 0, v[224:225]
	global_load_dwordx4 v[148:151], v[122:123], off nt
	global_load_dwordx4 v[136:139], v[122:123], off offset:256 nt
	s_mov_b64 s[16:17], 0xb0000
	v_lshl_add_u64 v[222:223], v[236:237], 0, s[16:17]
	v_lshl_add_u64 v[120:121], v[120:121], 0, v[222:223]
	global_load_dwordx4 v[132:135], v[120:121], off nt
	s_nop 0
	global_load_dwordx4 v[120:123], v[120:121], off offset:256 nt
	s_and_b64 vcc, exec, s[2:3]
	s_mov_b32 s30, s6
	s_mov_b32 s14, s8
	s_mov_b64 s[18:19], s[12:13]
	s_mov_b64 s[16:17], s[10:11]
	s_waitcnt vmcnt(0)
	v_cvt_f32_f16_e32 v250, v246
	v_cvt_f32_f16_sdwa v251, v246 dst_sel:DWORD dst_unused:UNUSED_PAD src0_sel:WORD_1
	v_pk_fma_f32 v[168:169], v[168:169], v[100:101], v[250:251]
	s_nop 0
	v_cvt_pk_f16_f32 v246, v168, v169
	v_cvt_f32_f16_e32 v168, v248
	v_cvt_f32_f16_sdwa v169, v248 dst_sel:DWORD dst_unused:UNUSED_PAD src0_sel:WORD_1
	v_pk_fma_f32 v[164:165], v[164:165], v[96:97], v[168:169]
	s_nop 0
	v_cvt_pk_f16_f32 v248, v164, v165
	v_cvt_f32_f16_e32 v164, v247
	v_cvt_f32_f16_sdwa v165, v247 dst_sel:DWORD dst_unused:UNUSED_PAD src0_sel:WORD_1
	v_pk_fma_f32 v[164:165], v[170:171], v[102:103], v[164:165]
	s_nop 0
	v_cvt_pk_f16_f32 v247, v164, v165
	v_cvt_f32_f16_e32 v164, v249
	v_cvt_f32_f16_sdwa v165, v249 dst_sel:DWORD dst_unused:UNUSED_PAD src0_sel:WORD_1
	v_pk_fma_f32 v[164:165], v[166:167], v[98:99], v[164:165]
	s_nop 0
	v_cvt_pk_f16_f32 v249, v164, v165
	v_lshl_add_u64 v[164:165], s[0:1], 0, v[236:237]
	v_lshl_add_u64 v[168:169], v[164:165], 0, v[220:221]
	v_cvt_f32_f16_e32 v164, v200
	v_cvt_f32_f16_sdwa v165, v200 dst_sel:DWORD dst_unused:UNUSED_PAD src0_sel:WORD_1
	global_store_dwordx4 v[168:169], v[246:249], off
	v_pk_fma_f32 v[144:145], v[144:145], v[88:89], v[164:165]
	s_nop 0
	v_cvt_pk_f16_f32 v164, v144, v145
	v_cvt_f32_f16_e32 v144, v202
	v_cvt_f32_f16_sdwa v145, v202 dst_sel:DWORD dst_unused:UNUSED_PAD src0_sel:WORD_1
	v_pk_fma_f32 v[140:141], v[140:141], v[80:81], v[144:145]
	s_nop 0
	v_cvt_pk_f16_f32 v166, v140, v141
	v_cvt_f32_f16_e32 v140, v201
	v_cvt_f32_f16_sdwa v141, v201 dst_sel:DWORD dst_unused:UNUSED_PAD src0_sel:WORD_1
	v_pk_fma_f32 v[140:141], v[146:147], v[90:91], v[140:141]
	s_nop 0
	v_cvt_pk_f16_f32 v165, v140, v141
	v_cvt_f32_f16_e32 v140, v203
	v_cvt_f32_f16_sdwa v141, v203 dst_sel:DWORD dst_unused:UNUSED_PAD src0_sel:WORD_1
	v_pk_fma_f32 v[140:141], v[142:143], v[82:83], v[140:141]
	s_nop 0
	v_cvt_pk_f16_f32 v167, v140, v141
	v_cvt_f32_f16_e32 v140, v196
	v_cvt_f32_f16_sdwa v141, v196 dst_sel:DWORD dst_unused:UNUSED_PAD src0_sel:WORD_1
	global_store_dwordx4 v[168:169], v[164:167], off offset:256
	v_pk_fma_f32 v[128:129], v[128:129], v[100:101], v[140:141]
	s_nop 0
	v_cvt_pk_f16_f32 v140, v128, v129
	v_cvt_f32_f16_e32 v128, v198
	v_cvt_f32_f16_sdwa v129, v198 dst_sel:DWORD dst_unused:UNUSED_PAD src0_sel:WORD_1
	v_pk_fma_f32 v[124:125], v[124:125], v[96:97], v[128:129]
	s_nop 0
	v_cvt_pk_f16_f32 v142, v124, v125
	v_cvt_f32_f16_e32 v124, v197
	v_cvt_f32_f16_sdwa v125, v197 dst_sel:DWORD dst_unused:UNUSED_PAD src0_sel:WORD_1
	v_pk_fma_f32 v[124:125], v[130:131], v[102:103], v[124:125]
	s_nop 0
	v_cvt_pk_f16_f32 v141, v124, v125
	v_cvt_f32_f16_e32 v124, v199
	v_cvt_f32_f16_sdwa v125, v199 dst_sel:DWORD dst_unused:UNUSED_PAD src0_sel:WORD_1
	v_pk_fma_f32 v[124:125], v[126:127], v[98:99], v[124:125]
	s_nop 0
	v_cvt_pk_f16_f32 v143, v124, v125
	v_lshl_add_u64 v[124:125], s[0:1], 0, v[234:235]
	v_lshl_add_u64 v[128:129], v[124:125], 0, v[220:221]
	v_cvt_f32_f16_e32 v124, v192
	v_cvt_f32_f16_sdwa v125, v192 dst_sel:DWORD dst_unused:UNUSED_PAD src0_sel:WORD_1
	global_store_dwordx4 v[128:129], v[140:143], off
	v_pk_fma_f32 v[116:117], v[116:117], v[88:89], v[124:125]
	s_nop 0
	v_cvt_pk_f16_f32 v124, v116, v117
	v_cvt_f32_f16_e32 v116, v194
	v_cvt_f32_f16_sdwa v117, v194 dst_sel:DWORD dst_unused:UNUSED_PAD src0_sel:WORD_1
	v_pk_fma_f32 v[112:113], v[112:113], v[80:81], v[116:117]
	s_nop 0
	v_cvt_pk_f16_f32 v126, v112, v113
	v_cvt_f32_f16_e32 v112, v193
	v_cvt_f32_f16_sdwa v113, v193 dst_sel:DWORD dst_unused:UNUSED_PAD src0_sel:WORD_1
	v_pk_fma_f32 v[112:113], v[118:119], v[90:91], v[112:113]
	s_nop 0
	v_cvt_pk_f16_f32 v125, v112, v113
	v_cvt_f32_f16_e32 v112, v195
	v_cvt_f32_f16_sdwa v113, v195 dst_sel:DWORD dst_unused:UNUSED_PAD src0_sel:WORD_1
	v_pk_fma_f32 v[112:113], v[114:115], v[82:83], v[112:113]
	s_nop 0
	v_cvt_pk_f16_f32 v127, v112, v113
	v_cvt_f32_f16_e32 v112, v188
	v_cvt_f32_f16_sdwa v113, v188 dst_sel:DWORD dst_unused:UNUSED_PAD src0_sel:WORD_1
	global_store_dwordx4 v[128:129], v[124:127], off offset:256
	v_pk_fma_f32 v[108:109], v[108:109], v[100:101], v[112:113]
	s_nop 0
	v_cvt_pk_f16_f32 v112, v108, v109
	v_cvt_f32_f16_e32 v108, v190
	v_cvt_f32_f16_sdwa v109, v190 dst_sel:DWORD dst_unused:UNUSED_PAD src0_sel:WORD_1
	v_pk_fma_f32 v[104:105], v[104:105], v[96:97], v[108:109]
	s_nop 0
	v_cvt_pk_f16_f32 v114, v104, v105
	v_cvt_f32_f16_e32 v104, v189
	v_cvt_f32_f16_sdwa v105, v189 dst_sel:DWORD dst_unused:UNUSED_PAD src0_sel:WORD_1
	v_pk_fma_f32 v[104:105], v[110:111], v[102:103], v[104:105]
	s_nop 0
	v_cvt_pk_f16_f32 v113, v104, v105
	v_cvt_f32_f16_e32 v104, v191
	v_cvt_f32_f16_sdwa v105, v191 dst_sel:DWORD dst_unused:UNUSED_PAD src0_sel:WORD_1
	v_pk_fma_f32 v[104:105], v[106:107], v[98:99], v[104:105]
	s_nop 0
	v_cvt_pk_f16_f32 v115, v104, v105
	v_lshl_add_u64 v[104:105], s[0:1], 0, v[232:233]
	v_lshl_add_u64 v[108:109], v[104:105], 0, v[220:221]
	v_cvt_f32_f16_e32 v104, v184
	v_cvt_f32_f16_sdwa v105, v184 dst_sel:DWORD dst_unused:UNUSED_PAD src0_sel:WORD_1
	global_store_dwordx4 v[108:109], v[112:115], off
	v_pk_fma_f32 v[92:93], v[92:93], v[88:89], v[104:105]
	s_nop 0
	v_cvt_pk_f16_f32 v104, v92, v93
	v_cvt_f32_f16_e32 v92, v186
	v_cvt_f32_f16_sdwa v93, v186 dst_sel:DWORD dst_unused:UNUSED_PAD src0_sel:WORD_1
	v_pk_fma_f32 v[84:85], v[84:85], v[80:81], v[92:93]
	s_nop 0
	v_cvt_pk_f16_f32 v106, v84, v85
	v_cvt_f32_f16_e32 v84, v185
	v_cvt_f32_f16_sdwa v85, v185 dst_sel:DWORD dst_unused:UNUSED_PAD src0_sel:WORD_1
	v_pk_fma_f32 v[84:85], v[94:95], v[90:91], v[84:85]
	s_nop 0
	v_cvt_pk_f16_f32 v105, v84, v85
	v_cvt_f32_f16_e32 v84, v187
	v_cvt_f32_f16_sdwa v85, v187 dst_sel:DWORD dst_unused:UNUSED_PAD src0_sel:WORD_1
	v_pk_fma_f32 v[84:85], v[86:87], v[82:83], v[84:85]
	s_nop 0
	v_cvt_pk_f16_f32 v107, v84, v85
	v_cvt_f32_f16_e32 v84, v180
	v_cvt_f32_f16_sdwa v85, v180 dst_sel:DWORD dst_unused:UNUSED_PAD src0_sel:WORD_1
	global_store_dwordx4 v[108:109], v[104:107], off offset:256
	v_pk_fma_f32 v[76:77], v[76:77], v[100:101], v[84:85]
	s_nop 0
	v_cvt_pk_f16_f32 v84, v76, v77
	v_cvt_f32_f16_e32 v76, v182
	v_cvt_f32_f16_sdwa v77, v182 dst_sel:DWORD dst_unused:UNUSED_PAD src0_sel:WORD_1
	v_pk_fma_f32 v[72:73], v[72:73], v[96:97], v[76:77]
	s_nop 0
	v_cvt_pk_f16_f32 v86, v72, v73
	v_cvt_f32_f16_e32 v72, v181
	v_cvt_f32_f16_sdwa v73, v181 dst_sel:DWORD dst_unused:UNUSED_PAD src0_sel:WORD_1
	v_pk_fma_f32 v[72:73], v[78:79], v[102:103], v[72:73]
	s_nop 0
	v_cvt_pk_f16_f32 v85, v72, v73
	v_cvt_f32_f16_e32 v72, v183
	v_cvt_f32_f16_sdwa v73, v183 dst_sel:DWORD dst_unused:UNUSED_PAD src0_sel:WORD_1
	v_pk_fma_f32 v[72:73], v[74:75], v[98:99], v[72:73]
	s_nop 0
	v_cvt_pk_f16_f32 v87, v72, v73
	v_lshl_add_u64 v[72:73], s[0:1], 0, v[230:231]
	v_lshl_add_u64 v[76:77], v[72:73], 0, v[220:221]
	v_cvt_f32_f16_e32 v72, v176
	v_cvt_f32_f16_sdwa v73, v176 dst_sel:DWORD dst_unused:UNUSED_PAD src0_sel:WORD_1
	global_store_dwordx4 v[76:77], v[84:87], off
	v_pk_fma_f32 v[68:69], v[68:69], v[88:89], v[72:73]
	s_nop 0
	v_cvt_pk_f16_f32 v72, v68, v69
	v_cvt_f32_f16_e32 v68, v178
	v_cvt_f32_f16_sdwa v69, v178 dst_sel:DWORD dst_unused:UNUSED_PAD src0_sel:WORD_1
	v_pk_fma_f32 v[64:65], v[64:65], v[80:81], v[68:69]
	s_nop 0
	v_cvt_pk_f16_f32 v74, v64, v65
	v_cvt_f32_f16_e32 v64, v177
	v_cvt_f32_f16_sdwa v65, v177 dst_sel:DWORD dst_unused:UNUSED_PAD src0_sel:WORD_1
	v_pk_fma_f32 v[64:65], v[70:71], v[90:91], v[64:65]
	s_nop 0
	v_cvt_pk_f16_f32 v73, v64, v65
	v_cvt_f32_f16_e32 v64, v179
	v_cvt_f32_f16_sdwa v65, v179 dst_sel:DWORD dst_unused:UNUSED_PAD src0_sel:WORD_1
	v_pk_fma_f32 v[64:65], v[66:67], v[82:83], v[64:65]
	s_nop 0
	v_cvt_pk_f16_f32 v75, v64, v65
	v_cvt_f32_f16_e32 v64, v172
	v_cvt_f32_f16_sdwa v65, v172 dst_sel:DWORD dst_unused:UNUSED_PAD src0_sel:WORD_1
	global_store_dwordx4 v[76:77], v[72:75], off offset:256
	v_pk_fma_f32 v[60:61], v[60:61], v[100:101], v[64:65]
	s_nop 0
	v_cvt_pk_f16_f32 v64, v60, v61
	v_cvt_f32_f16_e32 v60, v174
	v_cvt_f32_f16_sdwa v61, v174 dst_sel:DWORD dst_unused:UNUSED_PAD src0_sel:WORD_1
	v_pk_fma_f32 v[56:57], v[56:57], v[96:97], v[60:61]
	s_nop 0
	v_cvt_pk_f16_f32 v66, v56, v57
	v_cvt_f32_f16_e32 v56, v173
	v_cvt_f32_f16_sdwa v57, v173 dst_sel:DWORD dst_unused:UNUSED_PAD src0_sel:WORD_1
	v_pk_fma_f32 v[56:57], v[62:63], v[102:103], v[56:57]
	s_nop 0
	v_cvt_pk_f16_f32 v65, v56, v57
	v_cvt_f32_f16_e32 v56, v175
	v_cvt_f32_f16_sdwa v57, v175 dst_sel:DWORD dst_unused:UNUSED_PAD src0_sel:WORD_1
	v_pk_fma_f32 v[56:57], v[58:59], v[98:99], v[56:57]
	s_nop 0
	v_cvt_pk_f16_f32 v67, v56, v57
	v_lshl_add_u64 v[56:57], s[0:1], 0, v[228:229]
	v_lshl_add_u64 v[60:61], v[56:57], 0, v[220:221]
	v_cvt_f32_f16_e32 v56, v160
	v_cvt_f32_f16_sdwa v57, v160 dst_sel:DWORD dst_unused:UNUSED_PAD src0_sel:WORD_1
	global_store_dwordx4 v[60:61], v[64:67], off
	v_pk_fma_f32 v[52:53], v[52:53], v[88:89], v[56:57]
	s_nop 0
	v_cvt_pk_f16_f32 v56, v52, v53
	v_cvt_f32_f16_e32 v52, v162
	v_cvt_f32_f16_sdwa v53, v162 dst_sel:DWORD dst_unused:UNUSED_PAD src0_sel:WORD_1
	v_pk_fma_f32 v[48:49], v[48:49], v[80:81], v[52:53]
	s_nop 0
	v_cvt_pk_f16_f32 v58, v48, v49
	v_cvt_f32_f16_e32 v48, v161
	v_cvt_f32_f16_sdwa v49, v161 dst_sel:DWORD dst_unused:UNUSED_PAD src0_sel:WORD_1
	v_pk_fma_f32 v[48:49], v[54:55], v[90:91], v[48:49]
	s_nop 0
	v_cvt_pk_f16_f32 v57, v48, v49
	v_cvt_f32_f16_e32 v48, v163
	v_cvt_f32_f16_sdwa v49, v163 dst_sel:DWORD dst_unused:UNUSED_PAD src0_sel:WORD_1
	v_pk_fma_f32 v[48:49], v[50:51], v[82:83], v[48:49]
	s_nop 0
	v_cvt_pk_f16_f32 v59, v48, v49
	v_cvt_f32_f16_e32 v48, v156
	v_cvt_f32_f16_sdwa v49, v156 dst_sel:DWORD dst_unused:UNUSED_PAD src0_sel:WORD_1
	global_store_dwordx4 v[60:61], v[56:59], off offset:256
	v_pk_fma_f32 v[44:45], v[44:45], v[100:101], v[48:49]
	s_nop 0
	v_cvt_pk_f16_f32 v48, v44, v45
	v_cvt_f32_f16_e32 v44, v158
	v_cvt_f32_f16_sdwa v45, v158 dst_sel:DWORD dst_unused:UNUSED_PAD src0_sel:WORD_1
	v_pk_fma_f32 v[40:41], v[40:41], v[96:97], v[44:45]
	s_nop 0
	v_cvt_pk_f16_f32 v50, v40, v41
	v_cvt_f32_f16_e32 v40, v157
	v_cvt_f32_f16_sdwa v41, v157 dst_sel:DWORD dst_unused:UNUSED_PAD src0_sel:WORD_1
	v_pk_fma_f32 v[40:41], v[46:47], v[102:103], v[40:41]
	s_nop 0
	v_cvt_pk_f16_f32 v49, v40, v41
	v_cvt_f32_f16_e32 v40, v159
	v_cvt_f32_f16_sdwa v41, v159 dst_sel:DWORD dst_unused:UNUSED_PAD src0_sel:WORD_1
	v_pk_fma_f32 v[40:41], v[42:43], v[98:99], v[40:41]
	s_nop 0
	v_cvt_pk_f16_f32 v51, v40, v41
	v_lshl_add_u64 v[40:41], s[0:1], 0, v[226:227]
	v_lshl_add_u64 v[44:45], v[40:41], 0, v[220:221]
	v_cvt_f32_f16_e32 v40, v152
	v_cvt_f32_f16_sdwa v41, v152 dst_sel:DWORD dst_unused:UNUSED_PAD src0_sel:WORD_1
	global_store_dwordx4 v[44:45], v[48:51], off
	v_pk_fma_f32 v[36:37], v[36:37], v[88:89], v[40:41]
	s_nop 0
	v_cvt_pk_f16_f32 v40, v36, v37
	v_cvt_f32_f16_e32 v36, v154
	v_cvt_f32_f16_sdwa v37, v154 dst_sel:DWORD dst_unused:UNUSED_PAD src0_sel:WORD_1
	v_pk_fma_f32 v[32:33], v[32:33], v[80:81], v[36:37]
	s_nop 0
	v_cvt_pk_f16_f32 v42, v32, v33
	v_cvt_f32_f16_e32 v32, v153
	v_cvt_f32_f16_sdwa v33, v153 dst_sel:DWORD dst_unused:UNUSED_PAD src0_sel:WORD_1
	v_pk_fma_f32 v[32:33], v[38:39], v[90:91], v[32:33]
	s_nop 0
	v_cvt_pk_f16_f32 v41, v32, v33
	v_cvt_f32_f16_e32 v32, v155
	v_cvt_f32_f16_sdwa v33, v155 dst_sel:DWORD dst_unused:UNUSED_PAD src0_sel:WORD_1
	v_pk_fma_f32 v[32:33], v[34:35], v[82:83], v[32:33]
	s_nop 0
	v_cvt_pk_f16_f32 v43, v32, v33
	v_cvt_f32_f16_e32 v32, v148
	v_cvt_f32_f16_sdwa v33, v148 dst_sel:DWORD dst_unused:UNUSED_PAD src0_sel:WORD_1
	global_store_dwordx4 v[44:45], v[40:43], off offset:256
	v_pk_fma_f32 v[28:29], v[28:29], v[100:101], v[32:33]
	s_nop 0
	v_cvt_pk_f16_f32 v32, v28, v29
	v_cvt_f32_f16_e32 v28, v150
	v_cvt_f32_f16_sdwa v29, v150 dst_sel:DWORD dst_unused:UNUSED_PAD src0_sel:WORD_1
	v_pk_fma_f32 v[24:25], v[24:25], v[96:97], v[28:29]
	s_nop 0
	v_cvt_pk_f16_f32 v34, v24, v25
	v_cvt_f32_f16_e32 v24, v149
	v_cvt_f32_f16_sdwa v25, v149 dst_sel:DWORD dst_unused:UNUSED_PAD src0_sel:WORD_1
	v_pk_fma_f32 v[24:25], v[30:31], v[102:103], v[24:25]
	s_nop 0
	v_cvt_pk_f16_f32 v33, v24, v25
	v_cvt_f32_f16_e32 v24, v151
	v_cvt_f32_f16_sdwa v25, v151 dst_sel:DWORD dst_unused:UNUSED_PAD src0_sel:WORD_1
	v_pk_fma_f32 v[24:25], v[26:27], v[98:99], v[24:25]
	s_nop 0
	v_cvt_pk_f16_f32 v35, v24, v25
	v_lshl_add_u64 v[24:25], s[0:1], 0, v[224:225]
	v_lshl_add_u64 v[28:29], v[24:25], 0, v[220:221]
	v_cvt_f32_f16_e32 v24, v136
	v_cvt_f32_f16_sdwa v25, v136 dst_sel:DWORD dst_unused:UNUSED_PAD src0_sel:WORD_1
	global_store_dwordx4 v[28:29], v[32:35], off
	v_pk_fma_f32 v[20:21], v[20:21], v[88:89], v[24:25]
	s_nop 0
	v_cvt_pk_f16_f32 v24, v20, v21
	v_cvt_f32_f16_e32 v20, v138
	v_cvt_f32_f16_sdwa v21, v138 dst_sel:DWORD dst_unused:UNUSED_PAD src0_sel:WORD_1
	v_pk_fma_f32 v[16:17], v[16:17], v[80:81], v[20:21]
	s_nop 0
	v_cvt_pk_f16_f32 v26, v16, v17
	v_cvt_f32_f16_e32 v16, v137
	v_cvt_f32_f16_sdwa v17, v137 dst_sel:DWORD dst_unused:UNUSED_PAD src0_sel:WORD_1
	v_pk_fma_f32 v[16:17], v[22:23], v[90:91], v[16:17]
	s_nop 0
	v_cvt_pk_f16_f32 v25, v16, v17
	v_cvt_f32_f16_e32 v16, v139
	v_cvt_f32_f16_sdwa v17, v139 dst_sel:DWORD dst_unused:UNUSED_PAD src0_sel:WORD_1
	v_pk_fma_f32 v[16:17], v[18:19], v[82:83], v[16:17]
	s_nop 0
	v_cvt_pk_f16_f32 v27, v16, v17
	v_cvt_f32_f16_e32 v16, v132
	v_cvt_f32_f16_sdwa v17, v132 dst_sel:DWORD dst_unused:UNUSED_PAD src0_sel:WORD_1
	global_store_dwordx4 v[28:29], v[24:27], off offset:256
	v_pk_fma_f32 v[12:13], v[12:13], v[100:101], v[16:17]
	s_nop 0
	v_cvt_pk_f16_f32 v16, v12, v13
	v_cvt_f32_f16_e32 v12, v134
	v_cvt_f32_f16_sdwa v13, v134 dst_sel:DWORD dst_unused:UNUSED_PAD src0_sel:WORD_1
	v_pk_fma_f32 v[8:9], v[8:9], v[96:97], v[12:13]
	s_nop 0
	v_cvt_pk_f16_f32 v18, v8, v9
	v_cvt_f32_f16_e32 v8, v133
	v_cvt_f32_f16_sdwa v9, v133 dst_sel:DWORD dst_unused:UNUSED_PAD src0_sel:WORD_1
	v_pk_fma_f32 v[8:9], v[14:15], v[102:103], v[8:9]
	s_nop 0
	v_cvt_pk_f16_f32 v17, v8, v9
	v_cvt_f32_f16_e32 v8, v135
	v_cvt_f32_f16_sdwa v9, v135 dst_sel:DWORD dst_unused:UNUSED_PAD src0_sel:WORD_1
	v_pk_fma_f32 v[8:9], v[10:11], v[98:99], v[8:9]
	s_nop 0
	v_cvt_pk_f16_f32 v19, v8, v9
	v_lshl_add_u64 v[8:9], s[0:1], 0, v[222:223]
	v_lshl_add_u64 v[12:13], v[8:9], 0, v[220:221]
	v_cvt_f32_f16_e32 v8, v120
	v_cvt_f32_f16_sdwa v9, v120 dst_sel:DWORD dst_unused:UNUSED_PAD src0_sel:WORD_1
	global_store_dwordx4 v[12:13], v[16:19], off
	v_pk_fma_f32 v[4:5], v[4:5], v[88:89], v[8:9]
	s_nop 0
	v_cvt_pk_f16_f32 v8, v4, v5
	v_cvt_f32_f16_e32 v4, v122
	v_cvt_f32_f16_sdwa v5, v122 dst_sel:DWORD dst_unused:UNUSED_PAD src0_sel:WORD_1
	v_pk_fma_f32 v[0:1], v[0:1], v[80:81], v[4:5]
	s_nop 0
	v_cvt_pk_f16_f32 v10, v0, v1
	v_cvt_f32_f16_e32 v0, v121
	v_cvt_f32_f16_sdwa v1, v121 dst_sel:DWORD dst_unused:UNUSED_PAD src0_sel:WORD_1
	v_pk_fma_f32 v[0:1], v[6:7], v[90:91], v[0:1]
	s_nop 0
	v_cvt_pk_f16_f32 v9, v0, v1
	v_cvt_f32_f16_e32 v0, v123
	v_cvt_f32_f16_sdwa v1, v123 dst_sel:DWORD dst_unused:UNUSED_PAD src0_sel:WORD_1
	v_pk_fma_f32 v[0:1], v[2:3], v[82:83], v[0:1]
	s_nop 0
	v_cvt_pk_f16_f32 v11, v0, v1
	global_store_dwordx4 v[12:13], v[8:11], off offset:256
	s_cbranch_vccz .LBB0_640
	s_waitcnt vmcnt(0)
	s_cmpk_gt_u32 s22, 0xff
	s_cbranch_scc1 .LBB0_651
	s_barrier

.LBB0_1185:
	ds_read_b128 v[88:91], v243
	ds_read_b128 v[96:99], v243 offset:1024
	ds_read_b128 v[108:111], v243 offset:2048
	ds_read_b128 v[116:119], v243 offset:3072
	s_add_u32 s26, s24, 0xfff80080
	s_addc_u32 s27, s25, -1
	s_cmp_eq_u32 s64, 28
	s_cselect_b32 s29, s17, s27
	s_cselect_b32 s28, s31, s26
	s_cselect_b32 s27, s15, s63
	s_cselect_b32 s26, s61, s62
	s_add_i32 m0, s23, 0xc000
	ds_read_b128 v[128:131], v244
	ds_read_b128 v[136:139], v244 offset:1024
	ds_read_b128 v[144:147], v244 offset:2048
	ds_read_b128 v[148:151], v244 offset:3072
	ds_read_b128 v[152:155], v244 offset:4096
	ds_read_b128 v[164:167], v244 offset:5120
	ds_read_b128 v[168:171], v244 offset:6144
	ds_read_b128 v[172:175], v244 offset:7168
	global_load_lds_dwordx4 v212, s[24:25]
	s_add_i32 m0, s23, 0xe000
	s_nop 0
	global_load_lds_dwordx4 v214, s[24:25]
	s_barrier
	s_waitcnt lgkmcnt(0)
	v_mfma_f32_16x16x32_f16 v[160:163], v[88:91], v[128:131], v[160:163]
	v_mfma_f32_16x16x32_f16 v[156:159], v[108:111], v[128:131], v[156:159]
	v_mfma_f32_16x16x32_f16 v[124:127], v[88:91], v[144:147], v[124:127]
	v_mfma_f32_16x16x32_f16 v[120:123], v[108:111], v[144:147], v[120:123]
	v_mfma_f32_16x16x32_f16 v[100:103], v[88:91], v[152:155], v[100:103]
	v_mfma_f32_16x16x32_f16 v[92:95], v[108:111], v[152:155], v[92:95]
	v_mfma_f32_16x16x32_f16 v[76:79], v[88:91], v[168:171], v[76:79]
	v_mfma_f32_16x16x32_f16 v[72:75], v[108:111], v[168:171], v[72:75]
	v_mfma_f32_16x16x32_f16 v[160:163], v[96:99], v[136:139], v[160:163]
	v_mfma_f32_16x16x32_f16 v[156:159], v[116:119], v[136:139], v[156:159]
	v_mfma_f32_16x16x32_f16 v[124:127], v[96:99], v[148:151], v[124:127]
	v_mfma_f32_16x16x32_f16 v[120:123], v[116:119], v[148:151], v[120:123]
	v_mfma_f32_16x16x32_f16 v[100:103], v[96:99], v[164:167], v[100:103]
	v_mfma_f32_16x16x32_f16 v[92:95], v[116:119], v[164:167], v[92:95]
	v_mfma_f32_16x16x32_f16 v[76:79], v[96:99], v[172:175], v[76:79]
	v_mfma_f32_16x16x32_f16 v[72:75], v[116:119], v[172:175], v[72:75]
	s_barrier
	s_add_i32 s65, s59, s44
	s_add_u32 s72, s26, s6
	s_addc_u32 s73, s27, s7
	s_mov_b32 m0, s65
	ds_read_b128 v[176:179], v245
	ds_read_b128 v[180:183], v245 offset:1024
	ds_read_b128 v[184:187], v245 offset:2048
	ds_read_b128 v[188:191], v245 offset:3072
	global_load_lds_dwordx4 v206, s[26:27]
	s_add_i32 m0, s65, 0x2000
	s_nop 0
	global_load_lds_dwordx4 v210, s[26:27]
	s_barrier
	s_waitcnt lgkmcnt(0)
	v_mfma_f32_16x16x32_f16 v[140:143], v[176:179], v[128:131], v[140:143]
	v_mfma_f32_16x16x32_f16 v[112:115], v[176:179], v[144:147], v[112:115]
	v_mfma_f32_16x16x32_f16 v[104:107], v[184:187], v[144:147], v[104:107]
	v_mfma_f32_16x16x32_f16 v[84:87], v[176:179], v[152:155], v[84:87]
	v_mfma_f32_16x16x32_f16 v[80:83], v[184:187], v[152:155], v[80:83]
	v_mfma_f32_16x16x32_f16 v[68:71], v[176:179], v[168:171], v[68:71]
	v_mfma_f32_16x16x32_f16 v[64:67], v[184:187], v[168:171], v[64:67]
	v_mfma_f32_16x16x32_f16 v[140:143], v[180:183], v[136:139], v[140:143]
	v_mfma_f32_16x16x32_f16 v[128:131], v[184:187], v[128:131], v[132:135]
	v_mfma_f32_16x16x32_f16 v[112:115], v[180:183], v[148:151], v[112:115]
	v_mfma_f32_16x16x32_f16 v[104:107], v[188:191], v[148:151], v[104:107]
	v_mfma_f32_16x16x32_f16 v[84:87], v[180:183], v[164:167], v[84:87]
	v_mfma_f32_16x16x32_f16 v[80:83], v[188:191], v[164:167], v[80:83]
	v_mfma_f32_16x16x32_f16 v[68:71], v[180:183], v[172:175], v[68:71]
	v_mfma_f32_16x16x32_f16 v[64:67], v[188:191], v[172:175], v[64:67]
	v_mfma_f32_16x16x32_f16 v[128:131], v[188:191], v[136:139], v[128:131]
	s_barrier
	s_mov_b32 m0, s23
	s_add_u32 s74, s28, s6
	s_addc_u32 s75, s29, s7
	ds_read_b128 v[132:135], v244 offset:16384
	ds_read_b128 v[136:139], v244 offset:17408
	ds_read_b128 v[144:147], v244 offset:18432
	ds_read_b128 v[148:151], v244 offset:19456
	ds_read_b128 v[152:155], v244 offset:20480
	ds_read_b128 v[164:167], v244 offset:21504
	ds_read_b128 v[168:171], v244 offset:22528
	ds_read_b128 v[172:175], v244 offset:23552
	global_load_lds_dwordx4 v204, s[28:29]
	s_mov_b32 m0, s45
	s_nop 0
	global_load_lds_dwordx4 v208, s[28:29]
	s_barrier
	s_waitcnt lgkmcnt(0)
	v_mfma_f32_16x16x32_f16 v[60:63], v[88:91], v[132:135], v[60:63]
	v_mfma_f32_16x16x32_f16 v[56:59], v[108:111], v[132:135], v[56:59]
	v_mfma_f32_16x16x32_f16 v[44:47], v[88:91], v[144:147], v[44:47]
	v_mfma_f32_16x16x32_f16 v[40:43], v[108:111], v[144:147], v[40:43]
	v_mfma_f32_16x16x32_f16 v[28:31], v[88:91], v[152:155], v[28:31]
	v_mfma_f32_16x16x32_f16 v[24:27], v[108:111], v[152:155], v[24:27]
	v_mfma_f32_16x16x32_f16 v[12:15], v[88:91], v[168:171], v[12:15]
	v_mfma_f32_16x16x32_f16 v[8:11], v[108:111], v[168:171], v[8:11]
	v_mfma_f32_16x16x32_f16 v[60:63], v[96:99], v[136:139], v[60:63]
	v_mfma_f32_16x16x32_f16 v[56:59], v[116:119], v[136:139], v[56:59]
	v_mfma_f32_16x16x32_f16 v[44:47], v[96:99], v[148:151], v[44:47]
	v_mfma_f32_16x16x32_f16 v[40:43], v[116:119], v[148:151], v[40:43]
	v_mfma_f32_16x16x32_f16 v[28:31], v[96:99], v[164:167], v[28:31]
	v_mfma_f32_16x16x32_f16 v[24:27], v[116:119], v[164:167], v[24:27]
	v_mfma_f32_16x16x32_f16 v[12:15], v[96:99], v[172:175], v[12:15]
	v_mfma_f32_16x16x32_f16 v[8:11], v[116:119], v[172:175], v[8:11]
	s_barrier
	s_add_u32 s66, s26, 0x80000
	s_addc_u32 s67, s27, 0
	s_add_i32 s65, s60, s44
	s_mov_b32 m0, s65
	s_nop 0
	global_load_lds_dwordx4 v206, s[66:67]
	s_add_i32 m0, s65, 0x2000
	s_nop 0
	global_load_lds_dwordx4 v210, s[66:67]
	s_waitcnt vmcnt(6)
	s_barrier
	v_mfma_f32_16x16x32_f16 v[52:55], v[176:179], v[132:135], v[52:55]
	v_mfma_f32_16x16x32_f16 v[48:51], v[184:187], v[132:135], v[48:51]
	v_mfma_f32_16x16x32_f16 v[36:39], v[176:179], v[144:147], v[36:39]
	v_mfma_f32_16x16x32_f16 v[32:35], v[184:187], v[144:147], v[32:35]
	v_mfma_f32_16x16x32_f16 v[20:23], v[176:179], v[152:155], v[20:23]
	v_mfma_f32_16x16x32_f16 v[16:19], v[184:187], v[152:155], v[16:19]
	v_mfma_f32_16x16x32_f16 v[4:7], v[176:179], v[168:171], v[4:7]
	v_mfma_f32_16x16x32_f16 v[0:3], v[184:187], v[168:171], v[0:3]
	v_mfma_f32_16x16x32_f16 v[52:55], v[180:183], v[136:139], v[52:55]
	v_mfma_f32_16x16x32_f16 v[48:51], v[188:191], v[136:139], v[48:51]
	v_mfma_f32_16x16x32_f16 v[36:39], v[180:183], v[148:151], v[36:39]
	v_mfma_f32_16x16x32_f16 v[32:35], v[188:191], v[148:151], v[32:35]
	v_mfma_f32_16x16x32_f16 v[20:23], v[180:183], v[164:167], v[20:23]
	v_mfma_f32_16x16x32_f16 v[16:19], v[188:191], v[164:167], v[16:19]
	v_mfma_f32_16x16x32_f16 v[4:7], v[180:183], v[172:175], v[4:7]
	v_mfma_f32_16x16x32_f16 v[0:3], v[188:191], v[172:175], v[0:3]
	s_barrier
	s_add_i32 s65, 0, 0x18000
	v_add_u32_e32 v116, s65, v241
	ds_read_b128 v[88:91], v116
	ds_read_b128 v[96:99], v116 offset:1024
	ds_read_b128 v[108:111], v116 offset:2048
	ds_read_b128 v[116:119], v116 offset:3072
	s_add_u32 s28, s28, 0x80000
	s_addc_u32 s29, s29, 0
	s_mov_b32 m0, s48
	ds_read_b128 v[132:135], v244 offset:32768
	ds_read_b128 v[136:139], v244 offset:33792
	ds_read_b128 v[144:147], v244 offset:34816
	ds_read_b128 v[148:151], v244 offset:35840
	ds_read_b128 v[152:155], v244 offset:36864
	ds_read_b128 v[164:167], v244 offset:37888
	ds_read_b128 v[168:171], v244 offset:38912
	ds_read_b128 v[172:175], v244 offset:39936
	global_load_lds_dwordx4 v204, s[28:29]
	s_mov_b32 m0, s49
	s_nop 0
	global_load_lds_dwordx4 v208, s[28:29]
	s_barrier
	s_waitcnt lgkmcnt(0)
	v_mfma_f32_16x16x32_f16 v[160:163], v[88:91], v[132:135], v[160:163]
	v_mfma_f32_16x16x32_f16 v[156:159], v[108:111], v[132:135], v[156:159]
	v_mfma_f32_16x16x32_f16 v[124:127], v[88:91], v[144:147], v[124:127]
	v_mfma_f32_16x16x32_f16 v[120:123], v[108:111], v[144:147], v[120:123]
	v_mfma_f32_16x16x32_f16 v[100:103], v[88:91], v[152:155], v[100:103]
	v_mfma_f32_16x16x32_f16 v[92:95], v[108:111], v[152:155], v[92:95]
	v_mfma_f32_16x16x32_f16 v[76:79], v[88:91], v[168:171], v[76:79]
	v_mfma_f32_16x16x32_f16 v[72:75], v[108:111], v[168:171], v[72:75]
	v_mfma_f32_16x16x32_f16 v[160:163], v[96:99], v[136:139], v[160:163]
	v_mfma_f32_16x16x32_f16 v[156:159], v[116:119], v[136:139], v[156:159]
	v_mfma_f32_16x16x32_f16 v[124:127], v[96:99], v[148:151], v[124:127]
	v_mfma_f32_16x16x32_f16 v[120:123], v[116:119], v[148:151], v[120:123]
	v_mfma_f32_16x16x32_f16 v[100:103], v[96:99], v[164:167], v[100:103]
	v_mfma_f32_16x16x32_f16 v[92:95], v[116:119], v[164:167], v[92:95]
	v_mfma_f32_16x16x32_f16 v[76:79], v[96:99], v[172:175], v[76:79]
	v_mfma_f32_16x16x32_f16 v[72:75], v[116:119], v[172:175], v[72:75]
	s_barrier
	s_add_i32 s28, 0, 0x1c000
	s_add_i32 s29, s65, s44
	v_add_u32_e32 v188, s28, v241
	s_mov_b32 m0, s29
	ds_read_b128 v[176:179], v188
	ds_read_b128 v[180:183], v188 offset:1024
	ds_read_b128 v[184:187], v188 offset:2048
	ds_read_b128 v[188:191], v188 offset:3072
	global_load_lds_dwordx4 v206, s[72:73]
	s_add_i32 m0, s29, 0x2000
	s_nop 0
	global_load_lds_dwordx4 v210, s[72:73]
	s_barrier
	s_waitcnt lgkmcnt(0)
	v_mfma_f32_16x16x32_f16 v[140:143], v[176:179], v[132:135], v[140:143]
	v_mfma_f32_16x16x32_f16 v[128:131], v[184:187], v[132:135], v[128:131]
	v_mfma_f32_16x16x32_f16 v[112:115], v[176:179], v[144:147], v[112:115]
	v_mfma_f32_16x16x32_f16 v[104:107], v[184:187], v[144:147], v[104:107]
	v_mfma_f32_16x16x32_f16 v[84:87], v[176:179], v[152:155], v[84:87]
	v_mfma_f32_16x16x32_f16 v[80:83], v[184:187], v[152:155], v[80:83]
	v_mfma_f32_16x16x32_f16 v[68:71], v[176:179], v[168:171], v[68:71]
	v_mfma_f32_16x16x32_f16 v[64:67], v[184:187], v[168:171], v[64:67]
	v_mfma_f32_16x16x32_f16 v[140:143], v[180:183], v[136:139], v[140:143]
	v_mfma_f32_16x16x32_f16 v[132:135], v[188:191], v[136:139], v[128:131]
	v_mfma_f32_16x16x32_f16 v[112:115], v[180:183], v[148:151], v[112:115]
	v_mfma_f32_16x16x32_f16 v[104:107], v[188:191], v[148:151], v[104:107]
	v_mfma_f32_16x16x32_f16 v[84:87], v[180:183], v[164:167], v[84:87]
	v_mfma_f32_16x16x32_f16 v[80:83], v[188:191], v[164:167], v[80:83]
	v_mfma_f32_16x16x32_f16 v[68:71], v[180:183], v[172:175], v[68:71]
	v_mfma_f32_16x16x32_f16 v[64:67], v[188:191], v[172:175], v[64:67]
	s_barrier
	s_mov_b32 m0, s51
	ds_read_b128 v[128:131], v244 offset:49152
	ds_read_b128 v[136:139], v244 offset:50176
	ds_read_b128 v[144:147], v244 offset:51200
	ds_read_b128 v[148:151], v244 offset:52224
	ds_read_b128 v[152:155], v244 offset:53248
	ds_read_b128 v[164:167], v244 offset:54272
	ds_read_b128 v[168:171], v244 offset:55296
	ds_read_b128 v[172:175], v244 offset:56320
	global_load_lds_dwordx4 v204, s[74:75]
	s_mov_b32 m0, s54
	s_nop 0
	global_load_lds_dwordx4 v208, s[74:75]
	s_barrier
	s_waitcnt lgkmcnt(0)
	v_mfma_f32_16x16x32_f16 v[60:63], v[88:91], v[128:131], v[60:63]
	v_mfma_f32_16x16x32_f16 v[56:59], v[108:111], v[128:131], v[56:59]
	v_mfma_f32_16x16x32_f16 v[44:47], v[88:91], v[144:147], v[44:47]
	v_mfma_f32_16x16x32_f16 v[40:43], v[108:111], v[144:147], v[40:43]
	v_mfma_f32_16x16x32_f16 v[28:31], v[88:91], v[152:155], v[28:31]
	v_mfma_f32_16x16x32_f16 v[24:27], v[108:111], v[152:155], v[24:27]
	v_mfma_f32_16x16x32_f16 v[12:15], v[88:91], v[168:171], v[12:15]
	v_mfma_f32_16x16x32_f16 v[8:11], v[108:111], v[168:171], v[8:11]
	v_mfma_f32_16x16x32_f16 v[60:63], v[96:99], v[136:139], v[60:63]
	v_mfma_f32_16x16x32_f16 v[56:59], v[116:119], v[136:139], v[56:59]
	v_mfma_f32_16x16x32_f16 v[44:47], v[96:99], v[148:151], v[44:47]
	v_mfma_f32_16x16x32_f16 v[40:43], v[116:119], v[148:151], v[40:43]
	v_mfma_f32_16x16x32_f16 v[28:31], v[96:99], v[164:167], v[28:31]
	v_mfma_f32_16x16x32_f16 v[24:27], v[116:119], v[164:167], v[24:27]
	v_mfma_f32_16x16x32_f16 v[12:15], v[96:99], v[172:175], v[12:15]
	v_mfma_f32_16x16x32_f16 v[8:11], v[116:119], v[172:175], v[8:11]
	s_barrier
	s_add_u32 s26, s26, 0x80080
	s_addc_u32 s27, s27, 0
	s_add_i32 s28, s28, s44
	s_mov_b32 m0, s28
	s_nop 0
	global_load_lds_dwordx4 v206, s[26:27]
	s_add_i32 m0, s28, 0x2000
	s_nop 0
	global_load_lds_dwordx4 v210, s[26:27]
	s_waitcnt vmcnt(6)
	s_barrier
	v_mfma_f32_16x16x32_f16 v[52:55], v[176:179], v[128:131], v[52:55]
	v_mfma_f32_16x16x32_f16 v[48:51], v[184:187], v[128:131], v[48:51]
	v_mfma_f32_16x16x32_f16 v[36:39], v[176:179], v[144:147], v[36:39]
	v_mfma_f32_16x16x32_f16 v[32:35], v[184:187], v[144:147], v[32:35]
	v_mfma_f32_16x16x32_f16 v[20:23], v[176:179], v[152:155], v[20:23]
	v_mfma_f32_16x16x32_f16 v[16:19], v[184:187], v[152:155], v[16:19]
	v_mfma_f32_16x16x32_f16 v[4:7], v[176:179], v[168:171], v[4:7]
	v_mfma_f32_16x16x32_f16 v[0:3], v[184:187], v[168:171], v[0:3]
	v_mfma_f32_16x16x32_f16 v[52:55], v[180:183], v[136:139], v[52:55]
	v_mfma_f32_16x16x32_f16 v[48:51], v[188:191], v[136:139], v[48:51]
	v_mfma_f32_16x16x32_f16 v[36:39], v[180:183], v[148:151], v[36:39]
	v_mfma_f32_16x16x32_f16 v[32:35], v[188:191], v[148:151], v[32:35]
	v_mfma_f32_16x16x32_f16 v[20:23], v[180:183], v[164:167], v[20:23]
	v_mfma_f32_16x16x32_f16 v[16:19], v[188:191], v[164:167], v[16:19]
	v_mfma_f32_16x16x32_f16 v[4:7], v[180:183], v[172:175], v[4:7]
	v_mfma_f32_16x16x32_f16 v[0:3], v[188:191], v[172:175], v[0:3]
	s_barrier
	s_add_i32 s64, s64, 2
	s_add_u32 s24, s24, 0x100
	s_addc_u32 s25, s25, 0
	s_add_u32 s62, s62, 0x100
	s_addc_u32 s63, s63, 0
	s_cmp_gt_u32 s64, 29
	s_cbranch_scc0 .LBB0_1185
	s_setprio 0
	s_lshl_b32 s15, s22, 8
	s_add_i32 s17, s15, 0xffffe000
	s_lshr_b32 s17, s17, 11
	s_mulk_i32 s17, 0x1800
	s_addk_i32 s17, 0x1800
	s_cmp_gt_i32 s22, 31
	s_cselect_b32 s24, s17, 0
	s_ashr_i32 s25, s24, 31
	v_lshl_or_b32 v128, s30, 8, v242
	s_lshl_b64 s[24:25], s[24:25], 2
	s_add_u32 s24, s42, s24
	v_ashrrev_i32_e32 v129, 31, v128
	v_add_u32_e32 v130, s15, v240
	s_addc_u32 s25, s43, s25
	v_lshlrev_b64 v[220:221], 1, v[128:129]
	v_ashrrev_i32_e32 v131, 31, v130
	v_lshl_add_u64 v[96:97], v[128:129], 2, s[24:25]
	v_lshl_add_u64 v[128:129], s[4:5], 0, v[220:221]
	v_lshlrev_b64 v[236:237], 12, v[130:131]
	v_lshl_add_u64 v[136:137], v[128:129], 0, v[236:237]
	global_load_dwordx4 v[108:111], v[96:97], off offset:16
	global_load_dwordx4 v[116:119], v[96:97], off
	global_load_dwordx4 v[88:91], v[96:97], off offset:528
	s_nop 0
	global_load_dwordx4 v[96:99], v[96:97], off offset:512
	s_nop 0
	global_load_dwordx4 v[246:249], v[136:137], off nt
	global_load_dwordx4 v[200:203], v[136:137], off offset:256 nt
	v_or_b32_e32 v136, 16, v130
	v_ashrrev_i32_e32 v137, 31, v136
	v_lshlrev_b64 v[234:235], 12, v[136:137]
	v_lshl_add_u64 v[136:137], v[128:129], 0, v[234:235]
	global_load_dwordx4 v[196:199], v[136:137], off nt
	global_load_dwordx4 v[192:195], v[136:137], off offset:256 nt
	v_or_b32_e32 v136, 32, v130
	v_ashrrev_i32_e32 v137, 31, v136
	v_lshlrev_b64 v[232:233], 12, v[136:137]
	v_lshl_add_u64 v[136:137], v[128:129], 0, v[232:233]
	global_load_dwordx4 v[188:191], v[136:137], off nt
	global_load_dwordx4 v[184:187], v[136:137], off offset:256 nt
	v_readlane_b32 s64, v254, 21
	v_readlane_b32 s68, v254, 25
	v_readlane_b32 s69, v254, 26
	s_mov_b64 s[56:57], s[68:69]
	v_or_b32_e32 v130, 48, v130
	v_ashrrev_i32_e32 v131, 31, v130
	v_lshlrev_b64 v[230:231], 12, v[130:131]
	v_lshl_add_u64 v[130:131], v[128:129], 0, v[230:231]
	global_load_dwordx4 v[180:183], v[130:131], off nt
	global_load_dwordx4 v[176:179], v[130:131], off offset:256 nt
	v_lshl_add_u64 v[228:229], v[236:237], 0, s[0:1]
	v_lshl_add_u64 v[130:131], v[128:129], 0, v[228:229]
	global_load_dwordx4 v[172:175], v[130:131], off nt
	global_load_dwordx4 v[168:171], v[130:131], off offset:256 nt
	v_lshl_add_u64 v[226:227], v[236:237], 0, s[8:9]
	v_lshl_add_u64 v[130:131], v[128:129], 0, v[226:227]
	global_load_dwordx4 v[164:167], v[130:131], off nt
	global_load_dwordx4 v[152:155], v[130:131], off offset:256 nt
	v_lshl_add_u64 v[224:225], v[236:237], 0, s[10:11]
	v_lshl_add_u64 v[130:131], v[128:129], 0, v[224:225]
	global_load_dwordx4 v[148:151], v[130:131], off nt
	global_load_dwordx4 v[144:147], v[130:131], off offset:256 nt
	v_lshl_add_u64 v[222:223], v[236:237], 0, s[12:13]
	v_lshl_add_u64 v[128:129], v[128:129], 0, v[222:223]
	global_load_dwordx4 v[136:139], v[128:129], off nt
	s_nop 0
	global_load_dwordx4 v[128:131], v[128:129], off offset:256 nt
	s_and_b64 vcc, exec, s[2:3]
	s_mov_b32 s30, s14
	s_mov_b32 s22, s16
	s_mov_b64 s[26:27], s[20:21]
	s_mov_b64 s[24:25], s[18:19]
	v_readlane_b32 s65, v254, 22
	v_readlane_b32 s66, v254, 23
	v_readlane_b32 s67, v254, 24
	v_readlane_b32 s70, v254, 27
	v_readlane_b32 s71, v254, 28
	v_readlane_b32 s72, v254, 29
	v_readlane_b32 s73, v254, 30
	v_readlane_b32 s74, v254, 31
	v_readlane_b32 s75, v254, 32
	v_readlane_b32 s76, v254, 33
	v_readlane_b32 s77, v254, 34
	v_readlane_b32 s78, v254, 35
	v_readlane_b32 s79, v254, 36
	s_waitcnt vmcnt(0)
	v_cvt_f32_f16_e32 v250, v246
	v_cvt_f32_f16_sdwa v251, v246 dst_sel:DWORD dst_unused:UNUSED_PAD src0_sel:WORD_1
	v_pk_fma_f32 v[160:161], v[160:161], v[116:117], v[250:251]
	s_nop 0
	v_cvt_pk_f16_f32 v246, v160, v161
	v_cvt_f32_f16_e32 v160, v248
	v_cvt_f32_f16_sdwa v161, v248 dst_sel:DWORD dst_unused:UNUSED_PAD src0_sel:WORD_1
	v_pk_fma_f32 v[156:157], v[156:157], v[108:109], v[160:161]
	s_nop 0
	v_cvt_pk_f16_f32 v248, v156, v157
	v_cvt_f32_f16_e32 v156, v247
	v_cvt_f32_f16_sdwa v157, v247 dst_sel:DWORD dst_unused:UNUSED_PAD src0_sel:WORD_1
	v_pk_fma_f32 v[156:157], v[162:163], v[118:119], v[156:157]
	s_nop 0
	v_cvt_pk_f16_f32 v247, v156, v157
	v_cvt_f32_f16_e32 v156, v249
	v_cvt_f32_f16_sdwa v157, v249 dst_sel:DWORD dst_unused:UNUSED_PAD src0_sel:WORD_1
	v_pk_fma_f32 v[156:157], v[158:159], v[110:111], v[156:157]
	s_nop 0
	v_cvt_pk_f16_f32 v249, v156, v157
	v_lshl_add_u64 v[156:157], s[56:57], 0, v[236:237]
	v_lshl_add_u64 v[160:161], v[156:157], 0, v[220:221]
	v_cvt_f32_f16_e32 v156, v200
	v_cvt_f32_f16_sdwa v157, v200 dst_sel:DWORD dst_unused:UNUSED_PAD src0_sel:WORD_1
	global_store_dwordx4 v[160:161], v[246:249], off
	v_pk_fma_f32 v[140:141], v[140:141], v[96:97], v[156:157]
	s_nop 0
	v_cvt_pk_f16_f32 v156, v140, v141
	v_cvt_f32_f16_e32 v140, v202
	v_cvt_f32_f16_sdwa v141, v202 dst_sel:DWORD dst_unused:UNUSED_PAD src0_sel:WORD_1
	v_pk_fma_f32 v[132:133], v[132:133], v[88:89], v[140:141]
	s_nop 0
	v_cvt_pk_f16_f32 v158, v132, v133
	v_cvt_f32_f16_e32 v132, v201
	v_cvt_f32_f16_sdwa v133, v201 dst_sel:DWORD dst_unused:UNUSED_PAD src0_sel:WORD_1
	v_pk_fma_f32 v[132:133], v[142:143], v[98:99], v[132:133]
	s_nop 0
	v_cvt_pk_f16_f32 v157, v132, v133
	v_cvt_f32_f16_e32 v132, v203
	v_cvt_f32_f16_sdwa v133, v203 dst_sel:DWORD dst_unused:UNUSED_PAD src0_sel:WORD_1
	v_pk_fma_f32 v[132:133], v[134:135], v[90:91], v[132:133]
	s_nop 0
	v_cvt_pk_f16_f32 v159, v132, v133
	v_cvt_f32_f16_e32 v132, v196
	v_cvt_f32_f16_sdwa v133, v196 dst_sel:DWORD dst_unused:UNUSED_PAD src0_sel:WORD_1
	global_store_dwordx4 v[160:161], v[156:159], off offset:256
	v_pk_fma_f32 v[124:125], v[124:125], v[116:117], v[132:133]
	s_nop 0
	v_cvt_pk_f16_f32 v132, v124, v125
	v_cvt_f32_f16_e32 v124, v198
	v_cvt_f32_f16_sdwa v125, v198 dst_sel:DWORD dst_unused:UNUSED_PAD src0_sel:WORD_1
	v_pk_fma_f32 v[120:121], v[120:121], v[108:109], v[124:125]
	s_nop 0
	v_cvt_pk_f16_f32 v134, v120, v121
	v_cvt_f32_f16_e32 v120, v197
	v_cvt_f32_f16_sdwa v121, v197 dst_sel:DWORD dst_unused:UNUSED_PAD src0_sel:WORD_1
	v_pk_fma_f32 v[120:121], v[126:127], v[118:119], v[120:121]
	s_nop 0
	v_cvt_pk_f16_f32 v133, v120, v121
	v_cvt_f32_f16_e32 v120, v199
	v_cvt_f32_f16_sdwa v121, v199 dst_sel:DWORD dst_unused:UNUSED_PAD src0_sel:WORD_1
	v_pk_fma_f32 v[120:121], v[122:123], v[110:111], v[120:121]
	s_nop 0
	v_cvt_pk_f16_f32 v135, v120, v121
	v_lshl_add_u64 v[120:121], s[56:57], 0, v[234:235]
	v_lshl_add_u64 v[124:125], v[120:121], 0, v[220:221]
	v_cvt_f32_f16_e32 v120, v192
	v_cvt_f32_f16_sdwa v121, v192 dst_sel:DWORD dst_unused:UNUSED_PAD src0_sel:WORD_1
	global_store_dwordx4 v[124:125], v[132:135], off
	v_pk_fma_f32 v[112:113], v[112:113], v[96:97], v[120:121]
	s_nop 0
	v_cvt_pk_f16_f32 v120, v112, v113
	v_cvt_f32_f16_e32 v112, v194
	v_cvt_f32_f16_sdwa v113, v194 dst_sel:DWORD dst_unused:UNUSED_PAD src0_sel:WORD_1
	v_pk_fma_f32 v[104:105], v[104:105], v[88:89], v[112:113]
	s_nop 0
	v_cvt_pk_f16_f32 v122, v104, v105
	v_cvt_f32_f16_e32 v104, v193
	v_cvt_f32_f16_sdwa v105, v193 dst_sel:DWORD dst_unused:UNUSED_PAD src0_sel:WORD_1
	v_pk_fma_f32 v[104:105], v[114:115], v[98:99], v[104:105]
	s_nop 0
	v_cvt_pk_f16_f32 v121, v104, v105
	v_cvt_f32_f16_e32 v104, v195
	v_cvt_f32_f16_sdwa v105, v195 dst_sel:DWORD dst_unused:UNUSED_PAD src0_sel:WORD_1
	v_pk_fma_f32 v[104:105], v[106:107], v[90:91], v[104:105]
	s_nop 0
	v_cvt_pk_f16_f32 v123, v104, v105
	v_cvt_f32_f16_e32 v104, v188
	v_cvt_f32_f16_sdwa v105, v188 dst_sel:DWORD dst_unused:UNUSED_PAD src0_sel:WORD_1
	global_store_dwordx4 v[124:125], v[120:123], off offset:256
	v_pk_fma_f32 v[100:101], v[100:101], v[116:117], v[104:105]
	s_nop 0
	v_cvt_pk_f16_f32 v104, v100, v101
	v_cvt_f32_f16_e32 v100, v190
	v_cvt_f32_f16_sdwa v101, v190 dst_sel:DWORD dst_unused:UNUSED_PAD src0_sel:WORD_1
	v_pk_fma_f32 v[92:93], v[92:93], v[108:109], v[100:101]
	s_nop 0
	v_cvt_pk_f16_f32 v106, v92, v93
	v_cvt_f32_f16_e32 v92, v189
	v_cvt_f32_f16_sdwa v93, v189 dst_sel:DWORD dst_unused:UNUSED_PAD src0_sel:WORD_1
	v_pk_fma_f32 v[92:93], v[102:103], v[118:119], v[92:93]
	s_nop 0
	v_cvt_pk_f16_f32 v105, v92, v93
	v_cvt_f32_f16_e32 v92, v191
	v_cvt_f32_f16_sdwa v93, v191 dst_sel:DWORD dst_unused:UNUSED_PAD src0_sel:WORD_1
	v_pk_fma_f32 v[92:93], v[94:95], v[110:111], v[92:93]
	s_nop 0
	v_cvt_pk_f16_f32 v107, v92, v93
	v_lshl_add_u64 v[92:93], s[56:57], 0, v[232:233]
	v_lshl_add_u64 v[100:101], v[92:93], 0, v[220:221]
	v_cvt_f32_f16_e32 v92, v184
	v_cvt_f32_f16_sdwa v93, v184 dst_sel:DWORD dst_unused:UNUSED_PAD src0_sel:WORD_1
	global_store_dwordx4 v[100:101], v[104:107], off
	v_pk_fma_f32 v[84:85], v[84:85], v[96:97], v[92:93]
	s_nop 0
	v_cvt_pk_f16_f32 v92, v84, v85
	v_cvt_f32_f16_e32 v84, v186
	v_cvt_f32_f16_sdwa v85, v186 dst_sel:DWORD dst_unused:UNUSED_PAD src0_sel:WORD_1
	v_pk_fma_f32 v[80:81], v[80:81], v[88:89], v[84:85]
	s_nop 0
	v_cvt_pk_f16_f32 v94, v80, v81
	v_cvt_f32_f16_e32 v80, v185
	v_cvt_f32_f16_sdwa v81, v185 dst_sel:DWORD dst_unused:UNUSED_PAD src0_sel:WORD_1
	v_pk_fma_f32 v[80:81], v[86:87], v[98:99], v[80:81]
	s_nop 0
	v_cvt_pk_f16_f32 v93, v80, v81
	v_cvt_f32_f16_e32 v80, v187
	v_cvt_f32_f16_sdwa v81, v187 dst_sel:DWORD dst_unused:UNUSED_PAD src0_sel:WORD_1
	v_pk_fma_f32 v[80:81], v[82:83], v[90:91], v[80:81]
	s_nop 0
	v_cvt_pk_f16_f32 v95, v80, v81
	v_cvt_f32_f16_e32 v80, v180
	v_cvt_f32_f16_sdwa v81, v180 dst_sel:DWORD dst_unused:UNUSED_PAD src0_sel:WORD_1
	global_store_dwordx4 v[100:101], v[92:95], off offset:256
	v_pk_fma_f32 v[76:77], v[76:77], v[116:117], v[80:81]
	s_nop 0
	v_cvt_pk_f16_f32 v80, v76, v77
	v_cvt_f32_f16_e32 v76, v182
	v_cvt_f32_f16_sdwa v77, v182 dst_sel:DWORD dst_unused:UNUSED_PAD src0_sel:WORD_1
	v_pk_fma_f32 v[72:73], v[72:73], v[108:109], v[76:77]
	s_nop 0
	v_cvt_pk_f16_f32 v82, v72, v73
	v_cvt_f32_f16_e32 v72, v181
	v_cvt_f32_f16_sdwa v73, v181 dst_sel:DWORD dst_unused:UNUSED_PAD src0_sel:WORD_1
	v_pk_fma_f32 v[72:73], v[78:79], v[118:119], v[72:73]
	s_nop 0
	v_cvt_pk_f16_f32 v81, v72, v73
	v_cvt_f32_f16_e32 v72, v183
	v_cvt_f32_f16_sdwa v73, v183 dst_sel:DWORD dst_unused:UNUSED_PAD src0_sel:WORD_1
	v_pk_fma_f32 v[72:73], v[74:75], v[110:111], v[72:73]
	s_nop 0
	v_cvt_pk_f16_f32 v83, v72, v73
	v_lshl_add_u64 v[72:73], s[56:57], 0, v[230:231]
	v_lshl_add_u64 v[76:77], v[72:73], 0, v[220:221]
	v_cvt_f32_f16_e32 v72, v176
	v_cvt_f32_f16_sdwa v73, v176 dst_sel:DWORD dst_unused:UNUSED_PAD src0_sel:WORD_1
	global_store_dwordx4 v[76:77], v[80:83], off
	v_pk_fma_f32 v[68:69], v[68:69], v[96:97], v[72:73]
	s_nop 0
	v_cvt_pk_f16_f32 v72, v68, v69
	v_cvt_f32_f16_e32 v68, v178
	v_cvt_f32_f16_sdwa v69, v178 dst_sel:DWORD dst_unused:UNUSED_PAD src0_sel:WORD_1
	v_pk_fma_f32 v[64:65], v[64:65], v[88:89], v[68:69]
	s_nop 0
	v_cvt_pk_f16_f32 v74, v64, v65
	v_cvt_f32_f16_e32 v64, v177
	v_cvt_f32_f16_sdwa v65, v177 dst_sel:DWORD dst_unused:UNUSED_PAD src0_sel:WORD_1
	v_pk_fma_f32 v[64:65], v[70:71], v[98:99], v[64:65]
	s_nop 0
	v_cvt_pk_f16_f32 v73, v64, v65
	v_cvt_f32_f16_e32 v64, v179
	v_cvt_f32_f16_sdwa v65, v179 dst_sel:DWORD dst_unused:UNUSED_PAD src0_sel:WORD_1
	v_pk_fma_f32 v[64:65], v[66:67], v[90:91], v[64:65]
	s_nop 0
	v_cvt_pk_f16_f32 v75, v64, v65
	v_cvt_f32_f16_e32 v64, v172
	v_cvt_f32_f16_sdwa v65, v172 dst_sel:DWORD dst_unused:UNUSED_PAD src0_sel:WORD_1
	global_store_dwordx4 v[76:77], v[72:75], off offset:256
	v_pk_fma_f32 v[60:61], v[60:61], v[116:117], v[64:65]
	s_nop 0
	v_cvt_pk_f16_f32 v64, v60, v61
	v_cvt_f32_f16_e32 v60, v174
	v_cvt_f32_f16_sdwa v61, v174 dst_sel:DWORD dst_unused:UNUSED_PAD src0_sel:WORD_1
	v_pk_fma_f32 v[56:57], v[56:57], v[108:109], v[60:61]
	s_nop 0
	v_cvt_pk_f16_f32 v66, v56, v57
	v_cvt_f32_f16_e32 v56, v173
	v_cvt_f32_f16_sdwa v57, v173 dst_sel:DWORD dst_unused:UNUSED_PAD src0_sel:WORD_1
	v_pk_fma_f32 v[56:57], v[62:63], v[118:119], v[56:57]
	s_nop 0
	v_cvt_pk_f16_f32 v65, v56, v57
	v_cvt_f32_f16_e32 v56, v175
	v_cvt_f32_f16_sdwa v57, v175 dst_sel:DWORD dst_unused:UNUSED_PAD src0_sel:WORD_1
	v_pk_fma_f32 v[56:57], v[58:59], v[110:111], v[56:57]
	s_nop 0
	v_cvt_pk_f16_f32 v67, v56, v57
	v_lshl_add_u64 v[56:57], s[56:57], 0, v[228:229]
	v_lshl_add_u64 v[60:61], v[56:57], 0, v[220:221]
	v_cvt_f32_f16_e32 v56, v168
	v_cvt_f32_f16_sdwa v57, v168 dst_sel:DWORD dst_unused:UNUSED_PAD src0_sel:WORD_1
	global_store_dwordx4 v[60:61], v[64:67], off
	v_pk_fma_f32 v[52:53], v[52:53], v[96:97], v[56:57]
	s_nop 0
	v_cvt_pk_f16_f32 v56, v52, v53
	v_cvt_f32_f16_e32 v52, v170
	v_cvt_f32_f16_sdwa v53, v170 dst_sel:DWORD dst_unused:UNUSED_PAD src0_sel:WORD_1
	v_pk_fma_f32 v[48:49], v[48:49], v[88:89], v[52:53]
	s_nop 0
	v_cvt_pk_f16_f32 v58, v48, v49
	v_cvt_f32_f16_e32 v48, v169
	v_cvt_f32_f16_sdwa v49, v169 dst_sel:DWORD dst_unused:UNUSED_PAD src0_sel:WORD_1
	v_pk_fma_f32 v[48:49], v[54:55], v[98:99], v[48:49]
	s_nop 0
	v_cvt_pk_f16_f32 v57, v48, v49
	v_cvt_f32_f16_e32 v48, v171
	v_cvt_f32_f16_sdwa v49, v171 dst_sel:DWORD dst_unused:UNUSED_PAD src0_sel:WORD_1
	v_pk_fma_f32 v[48:49], v[50:51], v[90:91], v[48:49]
	s_nop 0
	v_cvt_pk_f16_f32 v59, v48, v49
	v_cvt_f32_f16_e32 v48, v164
	v_cvt_f32_f16_sdwa v49, v164 dst_sel:DWORD dst_unused:UNUSED_PAD src0_sel:WORD_1
	global_store_dwordx4 v[60:61], v[56:59], off offset:256
	v_pk_fma_f32 v[44:45], v[44:45], v[116:117], v[48:49]
	s_nop 0
	v_cvt_pk_f16_f32 v48, v44, v45
	v_cvt_f32_f16_e32 v44, v166
	v_cvt_f32_f16_sdwa v45, v166 dst_sel:DWORD dst_unused:UNUSED_PAD src0_sel:WORD_1
	v_pk_fma_f32 v[40:41], v[40:41], v[108:109], v[44:45]
	s_nop 0
	v_cvt_pk_f16_f32 v50, v40, v41
	v_cvt_f32_f16_e32 v40, v165
	v_cvt_f32_f16_sdwa v41, v165 dst_sel:DWORD dst_unused:UNUSED_PAD src0_sel:WORD_1
	v_pk_fma_f32 v[40:41], v[46:47], v[118:119], v[40:41]
	s_nop 0
	v_cvt_pk_f16_f32 v49, v40, v41
	v_cvt_f32_f16_e32 v40, v167
	v_cvt_f32_f16_sdwa v41, v167 dst_sel:DWORD dst_unused:UNUSED_PAD src0_sel:WORD_1
	v_pk_fma_f32 v[40:41], v[42:43], v[110:111], v[40:41]
	s_nop 0
	v_cvt_pk_f16_f32 v51, v40, v41
	v_lshl_add_u64 v[40:41], s[56:57], 0, v[226:227]
	v_lshl_add_u64 v[44:45], v[40:41], 0, v[220:221]
	v_cvt_f32_f16_e32 v40, v152
	v_cvt_f32_f16_sdwa v41, v152 dst_sel:DWORD dst_unused:UNUSED_PAD src0_sel:WORD_1
	global_store_dwordx4 v[44:45], v[48:51], off
	v_pk_fma_f32 v[36:37], v[36:37], v[96:97], v[40:41]
	s_nop 0
	v_cvt_pk_f16_f32 v40, v36, v37
	v_cvt_f32_f16_e32 v36, v154
	v_cvt_f32_f16_sdwa v37, v154 dst_sel:DWORD dst_unused:UNUSED_PAD src0_sel:WORD_1
	v_pk_fma_f32 v[32:33], v[32:33], v[88:89], v[36:37]
	s_nop 0
	v_cvt_pk_f16_f32 v42, v32, v33
	v_cvt_f32_f16_e32 v32, v153
	v_cvt_f32_f16_sdwa v33, v153 dst_sel:DWORD dst_unused:UNUSED_PAD src0_sel:WORD_1
	v_pk_fma_f32 v[32:33], v[38:39], v[98:99], v[32:33]
	s_nop 0
	v_cvt_pk_f16_f32 v41, v32, v33
	v_cvt_f32_f16_e32 v32, v155
	v_cvt_f32_f16_sdwa v33, v155 dst_sel:DWORD dst_unused:UNUSED_PAD src0_sel:WORD_1
	v_pk_fma_f32 v[32:33], v[34:35], v[90:91], v[32:33]
	s_nop 0
	v_cvt_pk_f16_f32 v43, v32, v33
	v_cvt_f32_f16_e32 v32, v148
	v_cvt_f32_f16_sdwa v33, v148 dst_sel:DWORD dst_unused:UNUSED_PAD src0_sel:WORD_1
	global_store_dwordx4 v[44:45], v[40:43], off offset:256
	v_pk_fma_f32 v[28:29], v[28:29], v[116:117], v[32:33]
	s_nop 0
	v_cvt_pk_f16_f32 v32, v28, v29
	v_cvt_f32_f16_e32 v28, v150
	v_cvt_f32_f16_sdwa v29, v150 dst_sel:DWORD dst_unused:UNUSED_PAD src0_sel:WORD_1
	v_pk_fma_f32 v[24:25], v[24:25], v[108:109], v[28:29]
	s_nop 0
	v_cvt_pk_f16_f32 v34, v24, v25
	v_cvt_f32_f16_e32 v24, v149
	v_cvt_f32_f16_sdwa v25, v149 dst_sel:DWORD dst_unused:UNUSED_PAD src0_sel:WORD_1
	v_pk_fma_f32 v[24:25], v[30:31], v[118:119], v[24:25]
	s_nop 0
	v_cvt_pk_f16_f32 v33, v24, v25
	v_cvt_f32_f16_e32 v24, v151
	v_cvt_f32_f16_sdwa v25, v151 dst_sel:DWORD dst_unused:UNUSED_PAD src0_sel:WORD_1
	v_pk_fma_f32 v[24:25], v[26:27], v[110:111], v[24:25]
	s_nop 0
	v_cvt_pk_f16_f32 v35, v24, v25
	v_lshl_add_u64 v[24:25], s[56:57], 0, v[224:225]
	v_lshl_add_u64 v[28:29], v[24:25], 0, v[220:221]
	v_cvt_f32_f16_e32 v24, v144
	v_cvt_f32_f16_sdwa v25, v144 dst_sel:DWORD dst_unused:UNUSED_PAD src0_sel:WORD_1
	global_store_dwordx4 v[28:29], v[32:35], off
	v_pk_fma_f32 v[20:21], v[20:21], v[96:97], v[24:25]
	s_nop 0
	v_cvt_pk_f16_f32 v24, v20, v21
	v_cvt_f32_f16_e32 v20, v146
	v_cvt_f32_f16_sdwa v21, v146 dst_sel:DWORD dst_unused:UNUSED_PAD src0_sel:WORD_1
	v_pk_fma_f32 v[16:17], v[16:17], v[88:89], v[20:21]
	s_nop 0
	v_cvt_pk_f16_f32 v26, v16, v17
	v_cvt_f32_f16_e32 v16, v145
	v_cvt_f32_f16_sdwa v17, v145 dst_sel:DWORD dst_unused:UNUSED_PAD src0_sel:WORD_1
	v_pk_fma_f32 v[16:17], v[22:23], v[98:99], v[16:17]
	s_nop 0
	v_cvt_pk_f16_f32 v25, v16, v17
	v_cvt_f32_f16_e32 v16, v147
	v_cvt_f32_f16_sdwa v17, v147 dst_sel:DWORD dst_unused:UNUSED_PAD src0_sel:WORD_1
	v_pk_fma_f32 v[16:17], v[18:19], v[90:91], v[16:17]
	s_nop 0
	v_cvt_pk_f16_f32 v27, v16, v17
	v_cvt_f32_f16_e32 v16, v136
	v_cvt_f32_f16_sdwa v17, v136 dst_sel:DWORD dst_unused:UNUSED_PAD src0_sel:WORD_1
	global_store_dwordx4 v[28:29], v[24:27], off offset:256
	v_pk_fma_f32 v[12:13], v[12:13], v[116:117], v[16:17]
	s_nop 0
	v_cvt_pk_f16_f32 v16, v12, v13
	v_cvt_f32_f16_e32 v12, v138
	v_cvt_f32_f16_sdwa v13, v138 dst_sel:DWORD dst_unused:UNUSED_PAD src0_sel:WORD_1
	v_pk_fma_f32 v[8:9], v[8:9], v[108:109], v[12:13]
	s_nop 0
	v_cvt_pk_f16_f32 v18, v8, v9
	v_cvt_f32_f16_e32 v8, v137
	v_cvt_f32_f16_sdwa v9, v137 dst_sel:DWORD dst_unused:UNUSED_PAD src0_sel:WORD_1
	v_pk_fma_f32 v[8:9], v[14:15], v[118:119], v[8:9]
	s_nop 0
	v_cvt_pk_f16_f32 v17, v8, v9
	v_cvt_f32_f16_e32 v8, v139
	v_cvt_f32_f16_sdwa v9, v139 dst_sel:DWORD dst_unused:UNUSED_PAD src0_sel:WORD_1
	v_pk_fma_f32 v[8:9], v[10:11], v[110:111], v[8:9]
	s_nop 0
	v_cvt_pk_f16_f32 v19, v8, v9
	v_lshl_add_u64 v[8:9], s[56:57], 0, v[222:223]
	v_lshl_add_u64 v[12:13], v[8:9], 0, v[220:221]
	v_cvt_f32_f16_e32 v8, v128
	v_cvt_f32_f16_sdwa v9, v128 dst_sel:DWORD dst_unused:UNUSED_PAD src0_sel:WORD_1
	global_store_dwordx4 v[12:13], v[16:19], off
	v_pk_fma_f32 v[4:5], v[4:5], v[96:97], v[8:9]
	s_nop 0
	v_cvt_pk_f16_f32 v8, v4, v5
	v_cvt_f32_f16_e32 v4, v130
	v_cvt_f32_f16_sdwa v5, v130 dst_sel:DWORD dst_unused:UNUSED_PAD src0_sel:WORD_1
	v_pk_fma_f32 v[0:1], v[0:1], v[88:89], v[4:5]
	s_nop 0
	v_cvt_pk_f16_f32 v10, v0, v1
	v_cvt_f32_f16_e32 v0, v129
	v_cvt_f32_f16_sdwa v1, v129 dst_sel:DWORD dst_unused:UNUSED_PAD src0_sel:WORD_1
	v_pk_fma_f32 v[0:1], v[6:7], v[98:99], v[0:1]
	s_nop 0
	v_cvt_pk_f16_f32 v9, v0, v1
	v_cvt_f32_f16_e32 v0, v131
	v_cvt_f32_f16_sdwa v1, v131 dst_sel:DWORD dst_unused:UNUSED_PAD src0_sel:WORD_1
	v_pk_fma_f32 v[0:1], v[2:3], v[90:91], v[0:1]
	s_nop 0
	v_cvt_pk_f16_f32 v11, v0, v1
	global_store_dwordx4 v[12:13], v[8:11], off offset:256
	s_cbranch_vccz .LBB0_1178
	s_waitcnt vmcnt(0)
	s_cmpk_gt_u32 s34, 0xff
	s_cbranch_scc1 .LBB0_1189
	s_barrier
